# as v25 plus: compute segments hold only MFMAs between their barriers (priority raise before the opening barrier, satisfied lgkmcnt wait dropped, priority drop after the closing barrier)
# speedup vs baseline: 1.0126x; 1.0053x over previous
.LBB0_382:
	s_add_i32 s39, s33, 1
	s_mov_b32 s47, s37
	s_add_i32 s37, s39, s35
	s_mul_i32 s37, s37, s23
	s_add_i32 s37, s37, s22
	s_mov_b32 s43, s38
	s_add_i32 s38, s37, 0xffffff28
	s_cmpk_lt_i32 s38, 0x48
	s_cselect_b64 s[76:77], -1, 0
	s_cmpk_gt_i32 s38, 0x47
	s_cselect_b64 s[72:73], -1, 0
	s_cmp_lt_i32 s38, 36
	s_cselect_b32 s41, 0, 0xffffffdc
	s_cselect_b32 s44, 0, 4
	s_add_i32 s38, s41, s38
	s_and_b32 s45, s37, 3
	s_ashr_i32 s37, s38, 2
	s_or_b32 s38, s45, s44
	s_or_b32 s38, s38, s28
	s_and_b64 s[44:45], s[76:77], exec
	s_cselect_b32 s80, s38, s43
	s_cselect_b32 s44, s37, s47
	s_ashr_i32 s81, s80, 31
	s_lshl_b64 s[50:51], s[80:81], 19
	s_add_u32 s74, s9, s50
	s_addc_u32 s75, s18, s51
	s_ashr_i32 s45, s44, 31
	s_lshl_b64 s[44:45], s[44:45], 19
	s_add_u32 s78, s14, s44
	s_addc_u32 s79, s15, s45
	s_add_u32 s84, s66, 0x100
	s_addc_u32 s85, s67, 0
	v_add_u32_e32 v142, 0x10000, v140
	v_add_u32_e32 v143, 0x14000, v140
	s_add_u32 s82, s66, 0x180
	ds_read_b128 v[4:7], v142
	ds_read_b128 v[8:11], v142 offset:1024
	ds_read_b128 v[12:15], v142 offset:2048
	ds_read_b128 v[16:19], v142 offset:3072
	ds_read_b128 v[20:23], v143
	ds_read_b128 v[24:27], v143 offset:1024
	ds_read_b128 v[28:31], v143 offset:2048
	ds_read_b128 v[32:35], v143 offset:3072
	s_addc_u32 s83, s67, 0
	s_and_b64 s[44:45], s[76:77], exec
	s_cselect_b32 s43, s75, s67
	s_cselect_b32 s44, s74, s66
	s_add_u32 s50, s12, 0x100
	s_addc_u32 s51, s13, 0
	s_and_b64 s[52:53], s[76:77], exec
	s_mov_b32 s41, 2
	s_cselect_b32 s45, s79, s13
	s_cselect_b32 s47, s78, s12
	ds_read_b128 v[36:39], v141
	ds_read_b128 v[40:43], v141 offset:1024
	ds_read_b128 v[44:47], v141 offset:2048
	ds_read_b128 v[48:51], v141 offset:3072
	ds_read_b128 v[52:55], v141 offset:4096
	ds_read_b128 v[56:59], v141 offset:5120
	ds_read_b128 v[60:63], v141 offset:6144
	ds_read_b128 v[64:67], v141 offset:7168
	s_add_u32 s52, s66, 0x40080
	s_addc_u32 s53, s67, 0
	s_add_i32 m0, s16, 0xc000
	s_nop 0
	global_load_lds_dwordx4 v136, s[52:53]
	s_nop 0
	s_add_i32 m0, s16, 0xe000
	s_nop 0
	global_load_lds_dwordx4 v137, s[52:53]
	s_waitcnt vmcnt(8)
	s_waitcnt lgkmcnt(0)
	s_setprio 1
	s_barrier
	v_mfma_f32_16x16x32_bf16 v[68:71], v[4:7], v[36:39], 0
	v_mfma_f32_16x16x32_bf16 v[72:75], v[12:15], v[36:39], 0
	s_waitcnt lgkmcnt(5)
	v_mfma_f32_16x16x32_bf16 v[76:79], v[4:7], v[44:47], 0
	v_mfma_f32_16x16x32_bf16 v[80:83], v[12:15], v[44:47], 0
	s_waitcnt lgkmcnt(3)
	v_mfma_f32_16x16x32_bf16 v[84:87], v[4:7], v[52:55], 0
	v_mfma_f32_16x16x32_bf16 v[88:91], v[12:15], v[52:55], 0
	s_waitcnt lgkmcnt(1)
	v_mfma_f32_16x16x32_bf16 v[92:95], v[4:7], v[60:63], 0
	v_mfma_f32_16x16x32_bf16 v[96:99], v[12:15], v[60:63], 0
	v_mfma_f32_16x16x32_bf16 v[68:71], v[8:11], v[40:43], v[68:71]
	v_mfma_f32_16x16x32_bf16 v[72:75], v[16:19], v[40:43], v[72:75]
	v_mfma_f32_16x16x32_bf16 v[76:79], v[8:11], v[48:51], v[76:79]
	v_mfma_f32_16x16x32_bf16 v[80:83], v[16:19], v[48:51], v[80:83]
	v_mfma_f32_16x16x32_bf16 v[84:87], v[8:11], v[56:59], v[84:87]
	v_mfma_f32_16x16x32_bf16 v[88:91], v[16:19], v[56:59], v[88:91]
	s_waitcnt lgkmcnt(0)
	v_mfma_f32_16x16x32_bf16 v[92:95], v[8:11], v[64:67], v[92:95]
	v_mfma_f32_16x16x32_bf16 v[100:103], v[16:19], v[64:67], v[96:99]
	s_setprio 0
	s_setprio 1
	v_mfma_f32_16x16x32_bf16 v[96:99], v[20:23], v[36:39], 0
	v_mfma_f32_16x16x32_bf16 v[36:39], v[28:31], v[36:39], 0
	v_mfma_f32_16x16x32_bf16 v[108:111], v[24:27], v[40:43], v[96:99]
	v_mfma_f32_16x16x32_bf16 v[36:39], v[32:35], v[40:43], v[36:39]
	v_mfma_f32_16x16x32_bf16 v[40:43], v[20:23], v[44:47], 0
	v_mfma_f32_16x16x32_bf16 v[44:47], v[28:31], v[44:47], 0
	v_mfma_f32_16x16x32_bf16 v[40:43], v[24:27], v[48:51], v[40:43]
	v_mfma_f32_16x16x32_bf16 v[44:47], v[32:35], v[48:51], v[44:47]
	v_mfma_f32_16x16x32_bf16 v[48:51], v[20:23], v[52:55], 0
	v_mfma_f32_16x16x32_bf16 v[52:55], v[28:31], v[52:55], 0
	v_mfma_f32_16x16x32_bf16 v[48:51], v[24:27], v[56:59], v[48:51]
	v_mfma_f32_16x16x32_bf16 v[52:55], v[32:35], v[56:59], v[52:55]
	v_mfma_f32_16x16x32_bf16 v[56:59], v[20:23], v[60:63], 0
	v_mfma_f32_16x16x32_bf16 v[146:149], v[24:27], v[64:67], v[56:59]
	v_mfma_f32_16x16x32_bf16 v[56:59], v[28:31], v[60:63], 0
	v_mfma_f32_16x16x32_bf16 v[150:153], v[32:35], v[64:67], v[56:59]
	s_barrier
	s_setprio 0
	s_nop 4
	ds_read_b128 v[56:59], v141 offset:16384
	ds_read_b128 v[60:63], v141 offset:17408
	ds_read_b128 v[64:67], v141 offset:18432
	ds_read_b128 v[96:99], v141 offset:19456
	ds_read_b128 v[104:107], v141 offset:20480
	ds_read_b128 v[112:115], v141 offset:21504
	ds_read_b128 v[116:119], v141 offset:22528
	ds_read_b128 v[120:123], v141 offset:23552
	s_add_i32 m0, s16, 0x10000
	s_nop 0
	global_load_lds_dwordx4 v1, s[50:51]
	s_nop 0
	s_add_i32 m0, s16, 0x12000
	s_nop 0
	global_load_lds_dwordx4 v134, s[50:51]
	s_add_u32 s50, s12, 0x40100
	s_addc_u32 s51, s13, 0
	s_add_i32 m0, s16, 0x14000
	s_nop 0
	global_load_lds_dwordx4 v1, s[50:51]
	s_nop 0
	s_add_i32 m0, s16, 0x16000
	s_nop 0
	global_load_lds_dwordx4 v134, s[50:51]
	s_nop 0
	s_add_i32 m0, s16, 0
	s_nop 0
	global_load_lds_dwordx4 v136, s[84:85]
	s_nop 0
	s_add_i32 m0, s16, 0x2000
	s_nop 0
	global_load_lds_dwordx4 v137, s[84:85]
	s_waitcnt vmcnt(8)
	s_waitcnt lgkmcnt(0)
	s_setprio 1
	s_barrier
	v_mfma_f32_16x16x32_bf16 v[124:127], v[4:7], v[56:59], 0
	s_waitcnt lgkmcnt(6)
	v_mfma_f32_16x16x32_bf16 v[154:157], v[8:11], v[60:63], v[124:127]
	v_mfma_f32_16x16x32_bf16 v[124:127], v[12:15], v[56:59], 0
	v_mfma_f32_16x16x32_bf16 v[158:161], v[16:19], v[60:63], v[124:127]
	s_waitcnt lgkmcnt(5)
	v_mfma_f32_16x16x32_bf16 v[124:127], v[4:7], v[64:67], 0
	s_waitcnt lgkmcnt(4)
	v_mfma_f32_16x16x32_bf16 v[162:165], v[8:11], v[96:99], v[124:127]
	v_mfma_f32_16x16x32_bf16 v[124:127], v[12:15], v[64:67], 0
	v_mfma_f32_16x16x32_bf16 v[166:169], v[16:19], v[96:99], v[124:127]
	s_waitcnt lgkmcnt(3)
	v_mfma_f32_16x16x32_bf16 v[124:127], v[4:7], v[104:107], 0
	s_waitcnt lgkmcnt(1)
	v_mfma_f32_16x16x32_bf16 v[4:7], v[4:7], v[116:119], 0
	v_mfma_f32_16x16x32_bf16 v[172:175], v[8:11], v[112:115], v[124:127]
	s_waitcnt lgkmcnt(0)
	v_mfma_f32_16x16x32_bf16 v[4:7], v[8:11], v[120:123], v[4:7]
	v_mfma_f32_16x16x32_bf16 v[8:11], v[12:15], v[116:119], 0
	v_mfma_f32_16x16x32_bf16 v[124:127], v[12:15], v[104:107], 0
	v_mfma_f32_16x16x32_bf16 v[8:11], v[16:19], v[120:123], v[8:11]
	v_mfma_f32_16x16x32_bf16 v[176:179], v[16:19], v[112:115], v[124:127]
	s_setprio 0
	s_setprio 1
	v_mfma_f32_16x16x32_bf16 v[16:19], v[28:31], v[56:59], 0
	v_mfma_f32_16x16x32_bf16 v[180:183], v[32:35], v[60:63], v[16:19]
	v_mfma_f32_16x16x32_bf16 v[16:19], v[20:23], v[64:67], 0
	v_mfma_f32_16x16x32_bf16 v[184:187], v[24:27], v[96:99], v[16:19]
	v_mfma_f32_16x16x32_bf16 v[16:19], v[28:31], v[64:67], 0
	v_mfma_f32_16x16x32_bf16 v[188:191], v[32:35], v[96:99], v[16:19]
	v_mfma_f32_16x16x32_bf16 v[16:19], v[20:23], v[104:107], 0
	v_mfma_f32_16x16x32_bf16 v[196:199], v[24:27], v[112:115], v[16:19]
	v_mfma_f32_16x16x32_bf16 v[16:19], v[28:31], v[104:107], 0
	v_mfma_f32_16x16x32_bf16 v[12:15], v[20:23], v[56:59], 0
	v_mfma_f32_16x16x32_bf16 v[200:203], v[32:35], v[112:115], v[16:19]
	v_mfma_f32_16x16x32_bf16 v[16:19], v[20:23], v[116:119], 0
	v_mfma_f32_16x16x32_bf16 v[12:15], v[24:27], v[60:63], v[12:15]
	v_mfma_f32_16x16x32_bf16 v[204:207], v[24:27], v[120:123], v[16:19]
	v_mfma_f32_16x16x32_bf16 v[16:19], v[28:31], v[116:119], 0
	v_mfma_f32_16x16x32_bf16 v[208:211], v[32:35], v[120:123], v[16:19]
	s_barrier
	s_setprio 0
	v_add_u32_e32 v144, 0x18000, v140
	v_add_u32_e32 v145, 0x1c000, v140
	s_nop 2
	ds_read_b128 v[16:19], v144
	ds_read_b128 v[20:23], v144 offset:1024
	ds_read_b128 v[28:31], v144 offset:2048
	ds_read_b128 v[212:215], v144 offset:3072
	ds_read_b128 v[216:219], v145
	ds_read_b128 v[220:223], v145 offset:1024
	ds_read_b128 v[224:227], v145 offset:2048
	ds_read_b128 v[228:231], v145 offset:3072
	ds_read_b128 v[24:27], v141 offset:32768
	ds_read_b128 v[32:35], v141 offset:33792
	ds_read_b128 v[60:63], v141 offset:34816
	ds_read_b128 v[232:235], v141 offset:35840
	ds_read_b128 v[236:239], v141 offset:36864
	ds_read_b128 v[240:243], v141 offset:37888
	ds_read_b128 v[244:247], v141 offset:38912
	ds_read_b128 v[248:251], v141 offset:39936
	s_add_u32 s50, s66, 0x40100
	s_addc_u32 s51, s67, 0
	s_add_i32 m0, s16, 0x4000
	s_nop 0
	global_load_lds_dwordx4 v136, s[50:51]
	s_nop 0
	s_add_i32 m0, s16, 0x6000
	s_nop 0
	global_load_lds_dwordx4 v137, s[50:51]
	s_waitcnt vmcnt(8)
	s_waitcnt lgkmcnt(0)
	s_setprio 1
	s_barrier
	v_mfma_f32_16x16x32_bf16 v[56:59], v[16:19], v[24:27], v[68:71]
	s_waitcnt lgkmcnt(6)
	v_mfma_f32_16x16x32_bf16 v[128:131], v[20:23], v[32:35], v[56:59]
	v_mfma_f32_16x16x32_bf16 v[56:59], v[28:31], v[24:27], v[72:75]
	v_mfma_f32_16x16x32_bf16 v[120:123], v[212:215], v[32:35], v[56:59]
	s_waitcnt lgkmcnt(5)
	v_mfma_f32_16x16x32_bf16 v[56:59], v[16:19], v[60:63], v[76:79]
	s_waitcnt lgkmcnt(4)
	v_mfma_f32_16x16x32_bf16 v[112:115], v[20:23], v[232:235], v[56:59]
	v_mfma_f32_16x16x32_bf16 v[56:59], v[28:31], v[60:63], v[80:83]
	v_mfma_f32_16x16x32_bf16 v[104:107], v[212:215], v[232:235], v[56:59]
	s_waitcnt lgkmcnt(3)
	v_mfma_f32_16x16x32_bf16 v[56:59], v[16:19], v[236:239], v[84:87]
	s_waitcnt lgkmcnt(2)
	v_mfma_f32_16x16x32_bf16 v[96:99], v[20:23], v[240:243], v[56:59]
	v_mfma_f32_16x16x32_bf16 v[56:59], v[28:31], v[236:239], v[88:91]
	v_mfma_f32_16x16x32_bf16 v[88:91], v[212:215], v[240:243], v[56:59]
	s_waitcnt lgkmcnt(1)
	v_mfma_f32_16x16x32_bf16 v[56:59], v[16:19], v[244:247], v[92:95]
	s_waitcnt lgkmcnt(0)
	v_mfma_f32_16x16x32_bf16 v[64:67], v[20:23], v[248:251], v[56:59]
	v_mfma_f32_16x16x32_bf16 v[56:59], v[28:31], v[244:247], v[100:103]
	v_mfma_f32_16x16x32_bf16 v[56:59], v[212:215], v[248:251], v[56:59]
	s_setprio 0
	s_setprio 1
	v_mfma_f32_16x16x32_bf16 v[68:71], v[216:219], v[24:27], v[108:111]
	v_mfma_f32_16x16x32_bf16 v[24:27], v[224:227], v[24:27], v[36:39]
	v_mfma_f32_16x16x32_bf16 v[116:119], v[228:231], v[32:35], v[24:27]
	v_mfma_f32_16x16x32_bf16 v[24:27], v[216:219], v[60:63], v[40:43]
	v_mfma_f32_16x16x32_bf16 v[108:111], v[220:223], v[232:235], v[24:27]
	v_mfma_f32_16x16x32_bf16 v[24:27], v[224:227], v[60:63], v[44:47]
	v_mfma_f32_16x16x32_bf16 v[100:103], v[228:231], v[232:235], v[24:27]
	v_mfma_f32_16x16x32_bf16 v[24:27], v[216:219], v[236:239], v[48:51]
	v_mfma_f32_16x16x32_bf16 v[92:95], v[220:223], v[240:243], v[24:27]
	v_mfma_f32_16x16x32_bf16 v[24:27], v[224:227], v[236:239], v[52:55]
	v_mfma_f32_16x16x32_bf16 v[84:87], v[228:231], v[240:243], v[24:27]
	v_mfma_f32_16x16x32_bf16 v[24:27], v[216:219], v[244:247], v[146:149]
	v_mfma_f32_16x16x32_bf16 v[60:63], v[220:223], v[248:251], v[24:27]
	v_mfma_f32_16x16x32_bf16 v[24:27], v[224:227], v[244:247], v[150:153]
	v_mfma_f32_16x16x32_bf16 v[124:127], v[220:223], v[32:35], v[68:71]
	v_mfma_f32_16x16x32_bf16 v[52:55], v[228:231], v[248:251], v[24:27]
	s_barrier
	s_setprio 0
	s_add_u32 s50, s12, 0x180
	ds_read_b128 v[36:39], v141 offset:49152
	ds_read_b128 v[44:47], v141 offset:50176
	ds_read_b128 v[146:149], v141 offset:51200
	ds_read_b128 v[150:153], v141 offset:52224
	ds_read_b128 v[232:235], v141 offset:53248
	ds_read_b128 v[236:239], v141 offset:54272
	ds_read_b128 v[240:243], v141 offset:55296
	ds_read_b128 v[244:247], v141 offset:56320
	s_addc_u32 s51, s13, 0
	s_add_i32 m0, s16, 0x18000
	s_nop 0
	global_load_lds_dwordx4 v1, s[50:51]
	s_nop 0
	s_add_i32 m0, s16, 0x1a000
	s_nop 0
	global_load_lds_dwordx4 v134, s[50:51]
	s_add_u32 s50, s12, 0x40180
	s_addc_u32 s51, s13, 0
	s_add_i32 m0, s16, 0x1c000
	s_nop 0
	global_load_lds_dwordx4 v1, s[50:51]
	s_nop 0
	s_add_i32 m0, s16, 0x1e000
	s_nop 0
	global_load_lds_dwordx4 v134, s[50:51]
	s_nop 0
	s_add_i32 m0, s16, 0x8000
	s_nop 0
	global_load_lds_dwordx4 v136, s[82:83]
	s_nop 0
	s_add_i32 m0, s16, 0xa000
	s_nop 0
	global_load_lds_dwordx4 v137, s[82:83]
	s_waitcnt vmcnt(8)
	s_waitcnt lgkmcnt(0)
	s_setprio 1
	s_barrier
	v_mfma_f32_16x16x32_bf16 v[24:27], v[16:19], v[36:39], v[154:157]
	s_waitcnt lgkmcnt(6)
	v_mfma_f32_16x16x32_bf16 v[80:83], v[20:23], v[44:47], v[24:27]
	v_mfma_f32_16x16x32_bf16 v[24:27], v[28:31], v[36:39], v[158:161]
	v_mfma_f32_16x16x32_bf16 v[72:75], v[212:215], v[44:47], v[24:27]
	s_waitcnt lgkmcnt(5)
	v_mfma_f32_16x16x32_bf16 v[24:27], v[16:19], v[146:149], v[162:165]
	s_waitcnt lgkmcnt(4)
	v_mfma_f32_16x16x32_bf16 v[48:51], v[20:23], v[150:153], v[24:27]
	v_mfma_f32_16x16x32_bf16 v[24:27], v[28:31], v[146:149], v[166:169]
	v_mfma_f32_16x16x32_bf16 v[40:43], v[212:215], v[150:153], v[24:27]
	s_waitcnt lgkmcnt(3)
	v_mfma_f32_16x16x32_bf16 v[24:27], v[16:19], v[232:235], v[172:175]
	s_waitcnt lgkmcnt(1)
	v_mfma_f32_16x16x32_bf16 v[4:7], v[16:19], v[240:243], v[4:7]
	v_mfma_f32_16x16x32_bf16 v[32:35], v[20:23], v[236:239], v[24:27]
	v_mfma_f32_16x16x32_bf16 v[24:27], v[28:31], v[232:235], v[176:179]
	s_waitcnt lgkmcnt(0)
	v_mfma_f32_16x16x32_bf16 v[16:19], v[20:23], v[244:247], v[4:7]
	v_mfma_f32_16x16x32_bf16 v[4:7], v[28:31], v[240:243], v[8:11]
	v_mfma_f32_16x16x32_bf16 v[24:27], v[212:215], v[236:239], v[24:27]
	v_mfma_f32_16x16x32_bf16 v[8:11], v[212:215], v[244:247], v[4:7]
	s_setprio 0
	s_setprio 1
	v_mfma_f32_16x16x32_bf16 v[4:7], v[216:219], v[36:39], v[12:15]
	v_mfma_f32_16x16x32_bf16 v[76:79], v[220:223], v[44:47], v[4:7]
	v_mfma_f32_16x16x32_bf16 v[4:7], v[224:227], v[36:39], v[180:183]
	v_mfma_f32_16x16x32_bf16 v[68:71], v[228:231], v[44:47], v[4:7]
	v_mfma_f32_16x16x32_bf16 v[4:7], v[216:219], v[146:149], v[184:187]
	v_mfma_f32_16x16x32_bf16 v[44:47], v[220:223], v[150:153], v[4:7]
	v_mfma_f32_16x16x32_bf16 v[4:7], v[224:227], v[146:149], v[188:191]
	v_mfma_f32_16x16x32_bf16 v[36:39], v[228:231], v[150:153], v[4:7]
	v_mfma_f32_16x16x32_bf16 v[4:7], v[216:219], v[232:235], v[196:199]
	v_mfma_f32_16x16x32_bf16 v[28:31], v[220:223], v[236:239], v[4:7]
	v_mfma_f32_16x16x32_bf16 v[4:7], v[224:227], v[232:235], v[200:203]
	v_mfma_f32_16x16x32_bf16 v[20:23], v[228:231], v[236:239], v[4:7]
	v_mfma_f32_16x16x32_bf16 v[4:7], v[216:219], v[240:243], v[204:207]
	v_mfma_f32_16x16x32_bf16 v[12:15], v[220:223], v[244:247], v[4:7]
	v_mfma_f32_16x16x32_bf16 v[4:7], v[224:227], v[240:243], v[208:211]
	v_mfma_f32_16x16x32_bf16 v[4:7], v[228:231], v[244:247], v[4:7]
	s_barrier
	s_setprio 0
	s_lshl_b32 s50, s80, 6
	s_addk_i32 s50, 0x4000
	s_lshl_b64 s[52:53], s[80:81], 14
	s_add_u32 s82, s6, s52
	s_addc_u32 s83, s7, s53
	s_lshl_b32 s51, s80, 8
	s_and_b32 s51, s51, 0x400
	s_add_i32 s51, s51, 0
	s_add_i32 s51, s51, 0x24400

.LBB0_402:
	s_lshl_b32 s54, s41, 7
	s_add_u32 s55, s66, s54
	s_addc_u32 s56, s67, 0
	s_add_u32 s58, s55, 0x100
	ds_read_b128 v[146:149], v142
	ds_read_b128 v[150:153], v142 offset:1024
	ds_read_b128 v[154:157], v142 offset:2048
	ds_read_b128 v[158:161], v142 offset:3072
	ds_read_b128 v[162:165], v143
	ds_read_b128 v[166:169], v143 offset:1024
	ds_read_b128 v[172:175], v143 offset:2048
	ds_read_b128 v[176:179], v143 offset:3072
	s_addc_u32 s59, s56, 0
	s_and_b64 s[52:53], s[84:85], exec
	s_cselect_b32 s91, s43, s59
	s_cselect_b32 s90, s44, s58
	s_add_u32 s52, s12, s54
	s_addc_u32 s53, s13, 0
	s_add_u32 s54, s52, 0x100
	s_addc_u32 s58, s53, 0
	s_and_b64 s[52:53], s[84:85], exec
	s_cselect_b32 s85, s45, s58
	s_cselect_b32 s84, s47, s54
	s_add_u32 s86, s90, 0x80
	s_addc_u32 s87, s91, 0
	s_waitcnt lgkmcnt(0)
	s_add_u32 s88, s84, 0x80
	s_addc_u32 s89, s85, 0
	ds_read_b128 v[180:183], v141
	ds_read_b128 v[184:187], v141 offset:1024
	ds_read_b128 v[188:191], v141 offset:2048
	ds_read_b128 v[196:199], v141 offset:3072
	ds_read_b128 v[200:203], v141 offset:4096
	ds_read_b128 v[204:207], v141 offset:5120
	ds_read_b128 v[208:211], v141 offset:6144
	ds_read_b128 v[212:215], v141 offset:7168
	s_add_u32 s52, s55, 0x40080
	s_addc_u32 s53, s56, 0
	s_add_i32 m0, s16, 0xc000
	s_nop 0
	global_load_lds_dwordx4 v136, s[52:53]
	s_nop 0
	s_add_i32 m0, s16, 0xe000
	s_nop 0
	global_load_lds_dwordx4 v137, s[52:53]
	s_waitcnt vmcnt(8)
	s_waitcnt lgkmcnt(0)
	s_setprio 1
	s_barrier
	v_mfma_f32_16x16x32_bf16 v[128:131], v[146:149], v[180:183], v[128:131]
	v_mfma_f32_16x16x32_bf16 v[120:123], v[154:157], v[180:183], v[120:123]
	s_waitcnt lgkmcnt(5)
	v_mfma_f32_16x16x32_bf16 v[112:115], v[146:149], v[188:191], v[112:115]
	v_mfma_f32_16x16x32_bf16 v[104:107], v[154:157], v[188:191], v[104:107]
	s_waitcnt lgkmcnt(3)
	v_mfma_f32_16x16x32_bf16 v[96:99], v[146:149], v[200:203], v[96:99]
	v_mfma_f32_16x16x32_bf16 v[88:91], v[154:157], v[200:203], v[88:91]
	s_waitcnt lgkmcnt(1)
	v_mfma_f32_16x16x32_bf16 v[64:67], v[146:149], v[208:211], v[64:67]
	v_mfma_f32_16x16x32_bf16 v[56:59], v[154:157], v[208:211], v[56:59]
	v_mfma_f32_16x16x32_bf16 v[128:131], v[150:153], v[184:187], v[128:131]
	v_mfma_f32_16x16x32_bf16 v[120:123], v[158:161], v[184:187], v[120:123]
	v_mfma_f32_16x16x32_bf16 v[112:115], v[150:153], v[196:199], v[112:115]
	v_mfma_f32_16x16x32_bf16 v[104:107], v[158:161], v[196:199], v[104:107]
	v_mfma_f32_16x16x32_bf16 v[96:99], v[150:153], v[204:207], v[96:99]
	v_mfma_f32_16x16x32_bf16 v[88:91], v[158:161], v[204:207], v[88:91]
	s_waitcnt lgkmcnt(0)
	v_mfma_f32_16x16x32_bf16 v[64:67], v[150:153], v[212:215], v[64:67]
	v_mfma_f32_16x16x32_bf16 v[56:59], v[158:161], v[212:215], v[56:59]
	s_setprio 0
	s_setprio 1
	v_mfma_f32_16x16x32_bf16 v[124:127], v[162:165], v[180:183], v[124:127]
	v_mfma_f32_16x16x32_bf16 v[116:119], v[172:175], v[180:183], v[116:119]
	v_mfma_f32_16x16x32_bf16 v[108:111], v[162:165], v[188:191], v[108:111]
	v_mfma_f32_16x16x32_bf16 v[100:103], v[172:175], v[188:191], v[100:103]
	v_mfma_f32_16x16x32_bf16 v[92:95], v[162:165], v[200:203], v[92:95]
	v_mfma_f32_16x16x32_bf16 v[84:87], v[172:175], v[200:203], v[84:87]
	v_mfma_f32_16x16x32_bf16 v[60:63], v[162:165], v[208:211], v[60:63]
	v_mfma_f32_16x16x32_bf16 v[52:55], v[172:175], v[208:211], v[52:55]
	v_mfma_f32_16x16x32_bf16 v[124:127], v[166:169], v[184:187], v[124:127]
	v_mfma_f32_16x16x32_bf16 v[116:119], v[176:179], v[184:187], v[116:119]
	v_mfma_f32_16x16x32_bf16 v[108:111], v[166:169], v[196:199], v[108:111]
	v_mfma_f32_16x16x32_bf16 v[100:103], v[176:179], v[196:199], v[100:103]
	v_mfma_f32_16x16x32_bf16 v[92:95], v[166:169], v[204:207], v[92:95]
	v_mfma_f32_16x16x32_bf16 v[84:87], v[176:179], v[204:207], v[84:87]
	v_mfma_f32_16x16x32_bf16 v[60:63], v[166:169], v[212:215], v[60:63]
	v_mfma_f32_16x16x32_bf16 v[52:55], v[176:179], v[212:215], v[52:55]
	s_barrier
	s_setprio 0
	ds_read_b128 v[180:183], v141 offset:16384
	ds_read_b128 v[184:187], v141 offset:17408
	ds_read_b128 v[188:191], v141 offset:18432
	ds_read_b128 v[196:199], v141 offset:19456
	ds_read_b128 v[200:203], v141 offset:20480
	ds_read_b128 v[204:207], v141 offset:21504
	ds_read_b128 v[208:211], v141 offset:22528
	ds_read_b128 v[212:215], v141 offset:23552
	s_add_i32 m0, s16, 0x10000
	s_nop 0
	global_load_lds_dwordx4 v1, s[84:85]
	s_nop 0
	s_add_i32 m0, s16, 0x12000
	s_nop 0
	global_load_lds_dwordx4 v134, s[84:85]
	s_add_u32 s52, s84, 0x40000
	s_addc_u32 s53, s85, 0
	s_add_i32 m0, s16, 0x14000
	s_nop 0
	global_load_lds_dwordx4 v1, s[52:53]
	s_nop 0
	s_add_i32 m0, s16, 0x16000
	s_nop 0
	global_load_lds_dwordx4 v134, s[52:53]
	s_nop 0
	s_add_i32 m0, s16, 0
	s_nop 0
	global_load_lds_dwordx4 v136, s[90:91]
	s_nop 0
	s_add_i32 m0, s16, 0x2000
	s_nop 0
	global_load_lds_dwordx4 v137, s[90:91]
	s_waitcnt vmcnt(8)
	s_waitcnt lgkmcnt(0)
	s_setprio 1
	s_barrier
	v_mfma_f32_16x16x32_bf16 v[80:83], v[146:149], v[180:183], v[80:83]
	v_mfma_f32_16x16x32_bf16 v[72:75], v[154:157], v[180:183], v[72:75]
	s_waitcnt lgkmcnt(5)
	v_mfma_f32_16x16x32_bf16 v[48:51], v[146:149], v[188:191], v[48:51]
	v_mfma_f32_16x16x32_bf16 v[40:43], v[154:157], v[188:191], v[40:43]
	s_waitcnt lgkmcnt(3)
	v_mfma_f32_16x16x32_bf16 v[32:35], v[146:149], v[200:203], v[32:35]
	v_mfma_f32_16x16x32_bf16 v[24:27], v[154:157], v[200:203], v[24:27]
	s_waitcnt lgkmcnt(1)
	v_mfma_f32_16x16x32_bf16 v[16:19], v[146:149], v[208:211], v[16:19]
	v_mfma_f32_16x16x32_bf16 v[8:11], v[154:157], v[208:211], v[8:11]
	v_mfma_f32_16x16x32_bf16 v[80:83], v[150:153], v[184:187], v[80:83]
	v_mfma_f32_16x16x32_bf16 v[72:75], v[158:161], v[184:187], v[72:75]
	v_mfma_f32_16x16x32_bf16 v[48:51], v[150:153], v[196:199], v[48:51]
	v_mfma_f32_16x16x32_bf16 v[40:43], v[158:161], v[196:199], v[40:43]
	v_mfma_f32_16x16x32_bf16 v[32:35], v[150:153], v[204:207], v[32:35]
	v_mfma_f32_16x16x32_bf16 v[24:27], v[158:161], v[204:207], v[24:27]
	s_waitcnt lgkmcnt(0)
	v_mfma_f32_16x16x32_bf16 v[16:19], v[150:153], v[212:215], v[16:19]
	v_mfma_f32_16x16x32_bf16 v[8:11], v[158:161], v[212:215], v[8:11]
	s_setprio 0
	s_setprio 1
	v_mfma_f32_16x16x32_bf16 v[76:79], v[162:165], v[180:183], v[76:79]
	v_mfma_f32_16x16x32_bf16 v[68:71], v[172:175], v[180:183], v[68:71]
	v_mfma_f32_16x16x32_bf16 v[44:47], v[162:165], v[188:191], v[44:47]
	v_mfma_f32_16x16x32_bf16 v[36:39], v[172:175], v[188:191], v[36:39]
	v_mfma_f32_16x16x32_bf16 v[28:31], v[162:165], v[200:203], v[28:31]
	v_mfma_f32_16x16x32_bf16 v[20:23], v[172:175], v[200:203], v[20:23]
	v_mfma_f32_16x16x32_bf16 v[12:15], v[162:165], v[208:211], v[12:15]
	v_mfma_f32_16x16x32_bf16 v[4:7], v[172:175], v[208:211], v[4:7]
	v_mfma_f32_16x16x32_bf16 v[76:79], v[166:169], v[184:187], v[76:79]
	v_mfma_f32_16x16x32_bf16 v[68:71], v[176:179], v[184:187], v[68:71]
	v_mfma_f32_16x16x32_bf16 v[44:47], v[166:169], v[196:199], v[44:47]
	v_mfma_f32_16x16x32_bf16 v[36:39], v[176:179], v[196:199], v[36:39]
	v_mfma_f32_16x16x32_bf16 v[28:31], v[166:169], v[204:207], v[28:31]
	v_mfma_f32_16x16x32_bf16 v[20:23], v[176:179], v[204:207], v[20:23]
	v_mfma_f32_16x16x32_bf16 v[12:15], v[166:169], v[212:215], v[12:15]
	v_mfma_f32_16x16x32_bf16 v[4:7], v[176:179], v[212:215], v[4:7]
	s_barrier
	s_setprio 0
	ds_read_b128 v[146:149], v144
	ds_read_b128 v[150:153], v144 offset:1024
	ds_read_b128 v[154:157], v144 offset:2048
	ds_read_b128 v[158:161], v144 offset:3072
	ds_read_b128 v[162:165], v145
	ds_read_b128 v[166:169], v145 offset:1024
	ds_read_b128 v[172:175], v145 offset:2048
	ds_read_b128 v[176:179], v145 offset:3072
	ds_read_b128 v[180:183], v141 offset:32768
	ds_read_b128 v[184:187], v141 offset:33792
	ds_read_b128 v[188:191], v141 offset:34816
	ds_read_b128 v[196:199], v141 offset:35840
	ds_read_b128 v[200:203], v141 offset:36864
	ds_read_b128 v[204:207], v141 offset:37888
	ds_read_b128 v[208:211], v141 offset:38912
	ds_read_b128 v[212:215], v141 offset:39936
	s_add_u32 s52, s90, 0x40000
	s_addc_u32 s53, s91, 0
	s_add_i32 m0, s16, 0x4000
	s_nop 0
	global_load_lds_dwordx4 v136, s[52:53]
	s_nop 0
	s_add_i32 m0, s16, 0x6000
	s_nop 0
	global_load_lds_dwordx4 v137, s[52:53]
	s_waitcnt vmcnt(8)
	s_waitcnt lgkmcnt(0)
	s_setprio 1
	s_barrier
	v_mfma_f32_16x16x32_bf16 v[128:131], v[146:149], v[180:183], v[128:131]
	v_mfma_f32_16x16x32_bf16 v[120:123], v[154:157], v[180:183], v[120:123]
	s_waitcnt lgkmcnt(5)
	v_mfma_f32_16x16x32_bf16 v[112:115], v[146:149], v[188:191], v[112:115]
	v_mfma_f32_16x16x32_bf16 v[104:107], v[154:157], v[188:191], v[104:107]
	s_waitcnt lgkmcnt(3)
	v_mfma_f32_16x16x32_bf16 v[96:99], v[146:149], v[200:203], v[96:99]
	v_mfma_f32_16x16x32_bf16 v[88:91], v[154:157], v[200:203], v[88:91]
	s_waitcnt lgkmcnt(1)
	v_mfma_f32_16x16x32_bf16 v[64:67], v[146:149], v[208:211], v[64:67]
	v_mfma_f32_16x16x32_bf16 v[56:59], v[154:157], v[208:211], v[56:59]
	v_mfma_f32_16x16x32_bf16 v[128:131], v[150:153], v[184:187], v[128:131]
	v_mfma_f32_16x16x32_bf16 v[120:123], v[158:161], v[184:187], v[120:123]
	v_mfma_f32_16x16x32_bf16 v[112:115], v[150:153], v[196:199], v[112:115]
	v_mfma_f32_16x16x32_bf16 v[104:107], v[158:161], v[196:199], v[104:107]
	v_mfma_f32_16x16x32_bf16 v[96:99], v[150:153], v[204:207], v[96:99]
	v_mfma_f32_16x16x32_bf16 v[88:91], v[158:161], v[204:207], v[88:91]
	s_waitcnt lgkmcnt(0)
	v_mfma_f32_16x16x32_bf16 v[64:67], v[150:153], v[212:215], v[64:67]
	v_mfma_f32_16x16x32_bf16 v[56:59], v[158:161], v[212:215], v[56:59]
	s_setprio 0
	s_setprio 1
	v_mfma_f32_16x16x32_bf16 v[124:127], v[162:165], v[180:183], v[124:127]
	v_mfma_f32_16x16x32_bf16 v[116:119], v[172:175], v[180:183], v[116:119]
	v_mfma_f32_16x16x32_bf16 v[108:111], v[162:165], v[188:191], v[108:111]
	v_mfma_f32_16x16x32_bf16 v[100:103], v[172:175], v[188:191], v[100:103]
	v_mfma_f32_16x16x32_bf16 v[92:95], v[162:165], v[200:203], v[92:95]
	v_mfma_f32_16x16x32_bf16 v[84:87], v[172:175], v[200:203], v[84:87]
	v_mfma_f32_16x16x32_bf16 v[60:63], v[162:165], v[208:211], v[60:63]
	v_mfma_f32_16x16x32_bf16 v[52:55], v[172:175], v[208:211], v[52:55]
	v_mfma_f32_16x16x32_bf16 v[124:127], v[166:169], v[184:187], v[124:127]
	v_mfma_f32_16x16x32_bf16 v[116:119], v[176:179], v[184:187], v[116:119]
	v_mfma_f32_16x16x32_bf16 v[108:111], v[166:169], v[196:199], v[108:111]
	v_mfma_f32_16x16x32_bf16 v[100:103], v[176:179], v[196:199], v[100:103]
	v_mfma_f32_16x16x32_bf16 v[92:95], v[166:169], v[204:207], v[92:95]
	v_mfma_f32_16x16x32_bf16 v[84:87], v[176:179], v[204:207], v[84:87]
	v_mfma_f32_16x16x32_bf16 v[60:63], v[166:169], v[212:215], v[60:63]
	v_mfma_f32_16x16x32_bf16 v[52:55], v[176:179], v[212:215], v[52:55]
	s_barrier
	s_setprio 0
	ds_read_b128 v[180:183], v141 offset:49152
	ds_read_b128 v[184:187], v141 offset:50176
	ds_read_b128 v[188:191], v141 offset:51200
	ds_read_b128 v[196:199], v141 offset:52224
	ds_read_b128 v[200:203], v141 offset:53248
	ds_read_b128 v[204:207], v141 offset:54272
	ds_read_b128 v[208:211], v141 offset:55296
	ds_read_b128 v[212:215], v141 offset:56320
	s_add_i32 m0, s16, 0x18000
	s_nop 0
	global_load_lds_dwordx4 v1, s[88:89]
	s_nop 0
	s_add_i32 m0, s16, 0x1a000
	s_nop 0
	global_load_lds_dwordx4 v134, s[88:89]
	s_add_u32 s52, s84, 0x40080
	s_addc_u32 s53, s85, 0
	s_add_i32 m0, s16, 0x1c000
	s_nop 0
	global_load_lds_dwordx4 v1, s[52:53]
	s_nop 0
	s_add_i32 m0, s16, 0x1e000
	s_nop 0
	global_load_lds_dwordx4 v134, s[52:53]
	s_nop 0
	s_add_i32 m0, s16, 0x8000
	s_nop 0
	global_load_lds_dwordx4 v136, s[86:87]
	s_nop 0
	s_add_i32 m0, s16, 0xa000
	s_nop 0
	global_load_lds_dwordx4 v137, s[86:87]
	s_waitcnt vmcnt(8)
	s_waitcnt lgkmcnt(0)
	s_setprio 1
	s_barrier
	v_mfma_f32_16x16x32_bf16 v[80:83], v[146:149], v[180:183], v[80:83]
	v_mfma_f32_16x16x32_bf16 v[72:75], v[154:157], v[180:183], v[72:75]
	s_waitcnt lgkmcnt(5)
	v_mfma_f32_16x16x32_bf16 v[48:51], v[146:149], v[188:191], v[48:51]
	v_mfma_f32_16x16x32_bf16 v[40:43], v[154:157], v[188:191], v[40:43]
	s_waitcnt lgkmcnt(3)
	v_mfma_f32_16x16x32_bf16 v[32:35], v[146:149], v[200:203], v[32:35]
	v_mfma_f32_16x16x32_bf16 v[24:27], v[154:157], v[200:203], v[24:27]
	s_waitcnt lgkmcnt(1)
	v_mfma_f32_16x16x32_bf16 v[16:19], v[146:149], v[208:211], v[16:19]
	v_mfma_f32_16x16x32_bf16 v[8:11], v[154:157], v[208:211], v[8:11]
	v_mfma_f32_16x16x32_bf16 v[80:83], v[150:153], v[184:187], v[80:83]
	v_mfma_f32_16x16x32_bf16 v[72:75], v[158:161], v[184:187], v[72:75]
	v_mfma_f32_16x16x32_bf16 v[48:51], v[150:153], v[196:199], v[48:51]
	v_mfma_f32_16x16x32_bf16 v[40:43], v[158:161], v[196:199], v[40:43]
	v_mfma_f32_16x16x32_bf16 v[32:35], v[150:153], v[204:207], v[32:35]
	v_mfma_f32_16x16x32_bf16 v[24:27], v[158:161], v[204:207], v[24:27]
	s_waitcnt lgkmcnt(0)
	v_mfma_f32_16x16x32_bf16 v[16:19], v[150:153], v[212:215], v[16:19]
	v_mfma_f32_16x16x32_bf16 v[8:11], v[158:161], v[212:215], v[8:11]
	s_setprio 0
	s_setprio 1
	v_mfma_f32_16x16x32_bf16 v[76:79], v[162:165], v[180:183], v[76:79]
	v_mfma_f32_16x16x32_bf16 v[68:71], v[172:175], v[180:183], v[68:71]
	v_mfma_f32_16x16x32_bf16 v[44:47], v[162:165], v[188:191], v[44:47]
	v_mfma_f32_16x16x32_bf16 v[36:39], v[172:175], v[188:191], v[36:39]
	v_mfma_f32_16x16x32_bf16 v[28:31], v[162:165], v[200:203], v[28:31]
	v_mfma_f32_16x16x32_bf16 v[20:23], v[172:175], v[200:203], v[20:23]
	v_mfma_f32_16x16x32_bf16 v[12:15], v[162:165], v[208:211], v[12:15]
	v_mfma_f32_16x16x32_bf16 v[4:7], v[172:175], v[208:211], v[4:7]
	v_mfma_f32_16x16x32_bf16 v[76:79], v[166:169], v[184:187], v[76:79]
	v_mfma_f32_16x16x32_bf16 v[68:71], v[176:179], v[184:187], v[68:71]
	v_mfma_f32_16x16x32_bf16 v[44:47], v[166:169], v[196:199], v[44:47]
	v_mfma_f32_16x16x32_bf16 v[36:39], v[176:179], v[196:199], v[36:39]
	v_mfma_f32_16x16x32_bf16 v[28:31], v[166:169], v[204:207], v[28:31]
	v_mfma_f32_16x16x32_bf16 v[20:23], v[176:179], v[204:207], v[20:23]
	v_mfma_f32_16x16x32_bf16 v[12:15], v[166:169], v[212:215], v[12:15]
	v_mfma_f32_16x16x32_bf16 v[4:7], v[176:179], v[212:215], v[4:7]
	s_barrier
	s_setprio 0
	s_add_i32 s52, s41, 2
	s_cmp_gt_u32 s41, 13
	s_cbranch_scc1 .LBB0_404
	s_mov_b32 s41, s52
	s_branch .LBB0_383

.LBB0_728:
	v_add_u32_e32 v137, 0x10000, v2
	v_add_u32_e32 v138, 0x14000, v2
	s_and_b64 s[2:3], exec, s[84:85]
	ds_read_b128 v[4:7], v137
	ds_read_b128 v[8:11], v137 offset:1024
	ds_read_b128 v[12:15], v137 offset:2048
	ds_read_b128 v[16:19], v137 offset:3072
	ds_read_b128 v[20:23], v138
	ds_read_b128 v[24:27], v138 offset:1024
	ds_read_b128 v[28:31], v138 offset:2048
	ds_read_b128 v[32:35], v138 offset:3072
	s_cselect_b32 s47, s6, s29
	s_add_u32 s12, s78, 0x100
	s_addc_u32 s13, s79, 0
	s_add_u32 s2, s78, 0x180
	s_addc_u32 s3, s79, 0
	s_add_u32 s6, s76, 0x100
	s_addc_u32 s7, s77, 0
	ds_read_b128 v[36:39], v136
	ds_read_b128 v[40:43], v136 offset:1024
	ds_read_b128 v[44:47], v136 offset:2048
	ds_read_b128 v[48:51], v136 offset:3072
	ds_read_b128 v[52:55], v136 offset:4096
	ds_read_b128 v[56:59], v136 offset:5120
	ds_read_b128 v[60:63], v136 offset:6144
	ds_read_b128 v[64:67], v136 offset:7168
	s_add_u32 s59, s78, s16
	s_addc_u32 s38, s79, 0
	s_add_u32 s26, s59, 0x80
	s_addc_u32 s27, s38, 0
	s_add_i32 m0, s43, 0xc000
	s_nop 0
	global_load_lds_dwordx4 v134, s[26:27]
	s_nop 0
	s_add_i32 m0, s43, 0xe000
	s_nop 0
	global_load_lds_dwordx4 v135, s[26:27]
	s_waitcnt vmcnt(8)
	s_waitcnt lgkmcnt(0)
	s_setprio 1
	s_barrier
	v_mfma_f32_16x16x32_bf16 v[86:89], v[4:7], v[52:55], 0
	s_waitcnt lgkmcnt(2)
	v_mfma_f32_16x16x32_bf16 v[94:97], v[8:11], v[56:59], v[86:89]
	v_mfma_f32_16x16x32_bf16 v[86:89], v[12:15], v[52:55], 0
	v_mfma_f32_16x16x32_bf16 v[98:101], v[16:19], v[56:59], v[86:89]
	s_waitcnt lgkmcnt(1)
	v_mfma_f32_16x16x32_bf16 v[86:89], v[4:7], v[60:63], 0
	v_mfma_f32_16x16x32_bf16 v[68:71], v[4:7], v[36:39], 0
	v_mfma_f32_16x16x32_bf16 v[72:75], v[12:15], v[36:39], 0
	v_mfma_f32_16x16x32_bf16 v[78:81], v[4:7], v[44:47], 0
	v_mfma_f32_16x16x32_bf16 v[82:85], v[12:15], v[44:47], 0
	s_waitcnt lgkmcnt(0)
	v_mfma_f32_16x16x32_bf16 v[102:105], v[8:11], v[64:67], v[86:89]
	v_mfma_f32_16x16x32_bf16 v[86:89], v[12:15], v[60:63], 0
	v_mfma_f32_16x16x32_bf16 v[68:71], v[8:11], v[40:43], v[68:71]
	v_mfma_f32_16x16x32_bf16 v[74:77], v[16:19], v[40:43], v[72:75]
	v_mfma_f32_16x16x32_bf16 v[78:81], v[8:11], v[48:51], v[78:81]
	v_mfma_f32_16x16x32_bf16 v[82:85], v[16:19], v[48:51], v[82:85]
	v_mfma_f32_16x16x32_bf16 v[106:109], v[16:19], v[64:67], v[86:89]
	s_setprio 0
	s_setprio 1
	v_mfma_f32_16x16x32_bf16 v[86:89], v[20:23], v[36:39], 0
	v_mfma_f32_16x16x32_bf16 v[36:39], v[28:31], v[36:39], 0
	v_mfma_f32_16x16x32_bf16 v[110:113], v[24:27], v[40:43], v[86:89]
	v_mfma_f32_16x16x32_bf16 v[36:39], v[32:35], v[40:43], v[36:39]
	v_mfma_f32_16x16x32_bf16 v[40:43], v[20:23], v[44:47], 0
	v_mfma_f32_16x16x32_bf16 v[44:47], v[28:31], v[44:47], 0
	v_mfma_f32_16x16x32_bf16 v[40:43], v[24:27], v[48:51], v[40:43]
	v_mfma_f32_16x16x32_bf16 v[44:47], v[32:35], v[48:51], v[44:47]
	v_mfma_f32_16x16x32_bf16 v[48:51], v[20:23], v[52:55], 0
	v_mfma_f32_16x16x32_bf16 v[52:55], v[28:31], v[52:55], 0
	v_mfma_f32_16x16x32_bf16 v[48:51], v[24:27], v[56:59], v[48:51]
	v_mfma_f32_16x16x32_bf16 v[52:55], v[32:35], v[56:59], v[52:55]
	v_mfma_f32_16x16x32_bf16 v[56:59], v[20:23], v[60:63], 0
	v_mfma_f32_16x16x32_bf16 v[60:63], v[28:31], v[60:63], 0
	v_mfma_f32_16x16x32_bf16 v[56:59], v[24:27], v[64:67], v[56:59]
	v_mfma_f32_16x16x32_bf16 v[60:63], v[32:35], v[64:67], v[60:63]
	s_barrier
	s_setprio 0
	ds_read_b128 v[64:67], v136 offset:16384
	ds_read_b128 v[86:89], v136 offset:17408
	ds_read_b128 v[90:93], v136 offset:18432
	ds_read_b128 v[114:117], v136 offset:19456
	ds_read_b128 v[118:121], v136 offset:20480
	ds_read_b128 v[122:125], v136 offset:21504
	ds_read_b128 v[126:129], v136 offset:22528
	ds_read_b128 v[130:133], v136 offset:23552
	s_add_i32 m0, s43, 0x10000
	s_nop 0
	global_load_lds_dwordx4 v134, s[6:7]
	s_nop 0
	s_add_i32 m0, s43, 0x12000
	s_nop 0
	global_load_lds_dwordx4 v135, s[6:7]
	s_add_u32 s6, s6, s16
	s_addc_u32 s7, s7, 0
	s_add_i32 m0, s43, 0x14000
	s_nop 0
	global_load_lds_dwordx4 v134, s[6:7]
	s_nop 0
	s_add_i32 m0, s43, 0x16000
	s_nop 0
	global_load_lds_dwordx4 v135, s[6:7]
	s_nop 0
	s_add_i32 m0, s43, 0
	s_nop 0
	global_load_lds_dwordx4 v134, s[12:13]
	s_nop 0
	s_add_i32 m0, s43, 0x2000
	s_nop 0
	global_load_lds_dwordx4 v135, s[12:13]
	s_waitcnt vmcnt(8)
	s_waitcnt lgkmcnt(0)
	s_setprio 1
	s_barrier
	v_mfma_f32_16x16x32_bf16 v[140:143], v[4:7], v[64:67], 0
	s_waitcnt lgkmcnt(5)
	v_mfma_f32_16x16x32_bf16 v[150:153], v[4:7], v[90:93], 0
	s_waitcnt lgkmcnt(3)
	v_mfma_f32_16x16x32_bf16 v[158:161], v[4:7], v[118:121], 0
	s_waitcnt lgkmcnt(1)
	v_mfma_f32_16x16x32_bf16 v[4:7], v[4:7], v[126:129], 0
	v_mfma_f32_16x16x32_bf16 v[146:149], v[12:15], v[64:67], 0
	v_mfma_f32_16x16x32_bf16 v[154:157], v[12:15], v[90:93], 0
	v_mfma_f32_16x16x32_bf16 v[162:165], v[12:15], v[118:121], 0
	s_waitcnt lgkmcnt(0)
	v_mfma_f32_16x16x32_bf16 v[166:169], v[8:11], v[130:133], v[4:7]
	v_mfma_f32_16x16x32_bf16 v[4:7], v[12:15], v[126:129], 0
	v_mfma_f32_16x16x32_bf16 v[142:145], v[8:11], v[86:89], v[140:143]
	v_mfma_f32_16x16x32_bf16 v[146:149], v[16:19], v[86:89], v[146:149]
	v_mfma_f32_16x16x32_bf16 v[150:153], v[8:11], v[114:117], v[150:153]
	v_mfma_f32_16x16x32_bf16 v[154:157], v[16:19], v[114:117], v[154:157]
	v_mfma_f32_16x16x32_bf16 v[158:161], v[8:11], v[122:125], v[158:161]
	v_mfma_f32_16x16x32_bf16 v[162:165], v[16:19], v[122:125], v[162:165]
	v_mfma_f32_16x16x32_bf16 v[172:175], v[16:19], v[130:133], v[4:7]
	s_setprio 0
	s_setprio 1
	v_mfma_f32_16x16x32_bf16 v[4:7], v[20:23], v[64:67], 0
	v_mfma_f32_16x16x32_bf16 v[176:179], v[24:27], v[86:89], v[4:7]
	v_mfma_f32_16x16x32_bf16 v[4:7], v[28:31], v[64:67], 0
	v_mfma_f32_16x16x32_bf16 v[64:67], v[32:35], v[86:89], v[4:7]
	v_mfma_f32_16x16x32_bf16 v[4:7], v[20:23], v[90:93], 0
	v_mfma_f32_16x16x32_bf16 v[180:183], v[24:27], v[114:117], v[4:7]
	v_mfma_f32_16x16x32_bf16 v[4:7], v[28:31], v[90:93], 0
	v_mfma_f32_16x16x32_bf16 v[184:187], v[32:35], v[114:117], v[4:7]
	v_mfma_f32_16x16x32_bf16 v[4:7], v[20:23], v[118:121], 0
	v_mfma_f32_16x16x32_bf16 v[196:199], v[24:27], v[122:125], v[4:7]
	v_mfma_f32_16x16x32_bf16 v[4:7], v[28:31], v[118:121], 0
	v_mfma_f32_16x16x32_bf16 v[200:203], v[32:35], v[122:125], v[4:7]
	v_mfma_f32_16x16x32_bf16 v[4:7], v[20:23], v[126:129], 0
	v_mfma_f32_16x16x32_bf16 v[204:207], v[24:27], v[130:133], v[4:7]
	v_mfma_f32_16x16x32_bf16 v[4:7], v[28:31], v[126:129], 0
	v_mfma_f32_16x16x32_bf16 v[208:211], v[32:35], v[130:133], v[4:7]
	s_barrier
	s_setprio 0
	v_add_u32_e32 v139, 0x18000, v2
	v_add_u32_e32 v140, 0x1c000, v2
	ds_read_b128 v[18:21], v139
	ds_read_b128 v[212:215], v139 offset:1024
	ds_read_b128 v[216:219], v139 offset:2048
	ds_read_b128 v[220:223], v139 offset:3072
	ds_read_b128 v[224:227], v140
	ds_read_b128 v[228:231], v140 offset:1024
	ds_read_b128 v[232:235], v140 offset:2048
	ds_read_b128 v[236:239], v140 offset:3072
	ds_read_b128 v[4:7], v136 offset:32768
	ds_read_b128 v[8:11], v136 offset:33792
	ds_read_b128 v[12:15], v136 offset:34816
	ds_read_b128 v[22:25], v136 offset:35840
	ds_read_b128 v[26:29], v136 offset:36864
	ds_read_b128 v[30:33], v136 offset:37888
	ds_read_b128 v[130:133], v136 offset:38912
	ds_read_b128 v[240:243], v136 offset:39936
	s_add_u32 s6, s12, s16
	s_addc_u32 s7, s13, 0
	s_add_i32 m0, s43, 0x4000
	s_nop 0
	global_load_lds_dwordx4 v134, s[6:7]
	s_nop 0
	s_add_i32 m0, s43, 0x6000
	s_nop 0
	global_load_lds_dwordx4 v135, s[6:7]
	s_waitcnt vmcnt(8)
	s_waitcnt lgkmcnt(0)
	s_setprio 1
	s_barrier
	v_mfma_f32_16x16x32_bf16 v[74:77], v[216:219], v[4:7], v[74:77]
	s_waitcnt lgkmcnt(6)
	v_mfma_f32_16x16x32_bf16 v[86:89], v[220:223], v[8:11], v[74:77]
	s_waitcnt lgkmcnt(5)
	v_mfma_f32_16x16x32_bf16 v[74:77], v[18:21], v[12:15], v[78:81]
	v_mfma_f32_16x16x32_bf16 v[78:81], v[216:219], v[12:15], v[82:85]
	s_waitcnt lgkmcnt(3)
	v_mfma_f32_16x16x32_bf16 v[82:85], v[216:219], v[26:29], v[98:101]
	v_mfma_f32_16x16x32_bf16 v[68:71], v[18:21], v[4:7], v[68:71]
	v_mfma_f32_16x16x32_bf16 v[90:93], v[220:223], v[22:25], v[78:81]
	v_mfma_f32_16x16x32_bf16 v[78:81], v[18:21], v[26:29], v[94:97]
	s_waitcnt lgkmcnt(2)
	v_mfma_f32_16x16x32_bf16 v[94:97], v[220:223], v[30:33], v[82:85]
	s_waitcnt lgkmcnt(1)
	v_mfma_f32_16x16x32_bf16 v[82:85], v[18:21], v[130:133], v[102:105]
	v_mfma_f32_16x16x32_bf16 v[98:101], v[216:219], v[130:133], v[106:109]
	v_mfma_f32_16x16x32_bf16 v[70:73], v[212:215], v[8:11], v[68:71]
	v_mfma_f32_16x16x32_bf16 v[74:77], v[212:215], v[22:25], v[74:77]
	v_mfma_f32_16x16x32_bf16 v[78:81], v[212:215], v[30:33], v[78:81]
	s_waitcnt lgkmcnt(0)
	v_mfma_f32_16x16x32_bf16 v[82:85], v[212:215], v[240:243], v[82:85]
	v_mfma_f32_16x16x32_bf16 v[98:101], v[220:223], v[240:243], v[98:101]
	s_setprio 0
	s_setprio 1
	v_mfma_f32_16x16x32_bf16 v[102:105], v[224:227], v[4:7], v[110:113]
	v_mfma_f32_16x16x32_bf16 v[4:7], v[232:235], v[4:7], v[36:39]
	v_mfma_f32_16x16x32_bf16 v[118:121], v[236:239], v[8:11], v[4:7]
	v_mfma_f32_16x16x32_bf16 v[4:7], v[224:227], v[12:15], v[40:43]
	v_mfma_f32_16x16x32_bf16 v[106:109], v[228:231], v[22:25], v[4:7]
	v_mfma_f32_16x16x32_bf16 v[4:7], v[232:235], v[12:15], v[44:47]
	v_mfma_f32_16x16x32_bf16 v[122:125], v[236:239], v[22:25], v[4:7]
	v_mfma_f32_16x16x32_bf16 v[4:7], v[224:227], v[26:29], v[48:51]
	v_mfma_f32_16x16x32_bf16 v[110:113], v[228:231], v[30:33], v[4:7]
	v_mfma_f32_16x16x32_bf16 v[4:7], v[232:235], v[26:29], v[52:55]
	v_mfma_f32_16x16x32_bf16 v[126:129], v[236:239], v[30:33], v[4:7]
	v_mfma_f32_16x16x32_bf16 v[4:7], v[224:227], v[130:133], v[56:59]
	v_mfma_f32_16x16x32_bf16 v[114:117], v[228:231], v[240:243], v[4:7]
	v_mfma_f32_16x16x32_bf16 v[4:7], v[232:235], v[130:133], v[60:63]
	v_mfma_f32_16x16x32_bf16 v[102:105], v[228:231], v[8:11], v[102:105]
	v_mfma_f32_16x16x32_bf16 v[130:133], v[236:239], v[240:243], v[4:7]
	s_barrier
	s_setprio 0
	s_add_u32 s6, s76, 0x180
	ds_read_b128 v[42:45], v136 offset:49152
	ds_read_b128 v[46:49], v136 offset:50176
	ds_read_b128 v[50:53], v136 offset:51200
	ds_read_b128 v[58:61], v136 offset:52224
	ds_read_b128 v[240:243], v136 offset:53248
	ds_read_b128 v[244:247], v136 offset:54272
	ds_read_b128 v[248:251], v136 offset:55296
	ds_read_b128 v[188:191], v136 offset:56320
	s_addc_u32 s7, s77, 0
	s_add_i32 m0, s43, 0x18000
	s_nop 0
	global_load_lds_dwordx4 v134, s[6:7]
	s_nop 0
	s_add_i32 m0, s43, 0x1a000
	s_nop 0
	global_load_lds_dwordx4 v135, s[6:7]
	s_add_u32 s6, s6, s16
	s_addc_u32 s7, s7, 0
	s_add_i32 m0, s43, 0x1c000
	s_nop 0
	global_load_lds_dwordx4 v134, s[6:7]
	s_nop 0
	s_add_i32 m0, s43, 0x1e000
	s_nop 0
	global_load_lds_dwordx4 v135, s[6:7]
	s_nop 0
	s_add_i32 m0, s43, 0x8000
	s_nop 0
	global_load_lds_dwordx4 v134, s[2:3]
	s_nop 0
	s_add_i32 m0, s43, 0xa000
	s_nop 0
	global_load_lds_dwordx4 v135, s[2:3]
	s_waitcnt vmcnt(8)
	s_waitcnt lgkmcnt(0)
	s_setprio 1
	s_barrier
	v_mfma_f32_16x16x32_bf16 v[10:13], v[216:219], v[42:45], v[146:149]
	s_waitcnt lgkmcnt(5)
	v_mfma_f32_16x16x32_bf16 v[14:17], v[216:219], v[50:53], v[154:157]
	v_mfma_f32_16x16x32_bf16 v[4:7], v[18:21], v[42:45], v[142:145]
	v_mfma_f32_16x16x32_bf16 v[22:25], v[220:223], v[46:49], v[10:13]
	v_mfma_f32_16x16x32_bf16 v[10:13], v[18:21], v[50:53], v[150:153]
	s_waitcnt lgkmcnt(4)
	v_mfma_f32_16x16x32_bf16 v[26:29], v[220:223], v[58:61], v[14:17]
	s_waitcnt lgkmcnt(3)
	v_mfma_f32_16x16x32_bf16 v[14:17], v[18:21], v[240:243], v[158:161]
	v_mfma_f32_16x16x32_bf16 v[30:33], v[216:219], v[240:243], v[162:165]
	s_waitcnt lgkmcnt(1)
	v_mfma_f32_16x16x32_bf16 v[18:21], v[18:21], v[248:251], v[166:169]
	v_mfma_f32_16x16x32_bf16 v[34:37], v[216:219], v[248:251], v[172:175]
	v_mfma_f32_16x16x32_bf16 v[6:9], v[212:215], v[46:49], v[4:7]
	v_mfma_f32_16x16x32_bf16 v[10:13], v[212:215], v[58:61], v[10:13]
	v_mfma_f32_16x16x32_bf16 v[14:17], v[212:215], v[244:247], v[14:17]
	v_mfma_f32_16x16x32_bf16 v[30:33], v[220:223], v[244:247], v[30:33]
	s_waitcnt lgkmcnt(0)
	v_mfma_f32_16x16x32_bf16 v[18:21], v[212:215], v[188:191], v[18:21]
	v_mfma_f32_16x16x32_bf16 v[34:37], v[220:223], v[188:191], v[34:37]
	s_setprio 0
	s_setprio 1
	v_mfma_f32_16x16x32_bf16 v[38:41], v[224:227], v[42:45], v[176:179]
	v_mfma_f32_16x16x32_bf16 v[42:45], v[232:235], v[42:45], v[64:67]
	v_mfma_f32_16x16x32_bf16 v[38:41], v[228:231], v[46:49], v[38:41]
	v_mfma_f32_16x16x32_bf16 v[54:57], v[236:239], v[46:49], v[42:45]
	v_mfma_f32_16x16x32_bf16 v[42:45], v[224:227], v[50:53], v[180:183]
	v_mfma_f32_16x16x32_bf16 v[46:49], v[232:235], v[50:53], v[184:187]
	v_mfma_f32_16x16x32_bf16 v[50:53], v[232:235], v[240:243], v[200:203]
	v_mfma_f32_16x16x32_bf16 v[42:45], v[228:231], v[58:61], v[42:45]
	v_mfma_f32_16x16x32_bf16 v[58:61], v[236:239], v[58:61], v[46:49]
	v_mfma_f32_16x16x32_bf16 v[46:49], v[224:227], v[240:243], v[196:199]
	v_mfma_f32_16x16x32_bf16 v[62:65], v[236:239], v[244:247], v[50:53]
	v_mfma_f32_16x16x32_bf16 v[50:53], v[224:227], v[248:251], v[204:207]
	v_mfma_f32_16x16x32_bf16 v[66:69], v[232:235], v[248:251], v[208:211]
	v_mfma_f32_16x16x32_bf16 v[46:49], v[228:231], v[244:247], v[46:49]
	v_mfma_f32_16x16x32_bf16 v[50:53], v[228:231], v[188:191], v[50:53]
	v_mfma_f32_16x16x32_bf16 v[66:69], v[236:239], v[188:191], v[66:69]
	s_barrier
	s_setprio 0
	s_add_i32 s2, s47, 1
	s_lshl_b32 s72, s47, 6
	s_and_b32 s3, s2, 31
	s_lshl_b32 s2, s2, 6
	s_add_i32 s6, s72, 0x9000
	s_add_i32 s7, s72, 0x8000
	s_add_i32 s18, s72, 0x7000
	s_addk_i32 s2, 0x6000
	s_cmp_eq_u32 s3, 0
	s_cselect_b32 s26, 0, 32
	s_cselect_b32 s27, 0, s2
	s_add_i32 s40, s72, 0x6000
	s_add_i32 s41, s72, 0x5000
	s_and_b32 s2, s47, 31
	s_add_i32 s3, s72, 0x4fc0
	s_cmp_eq_u32 s2, 0
	s_cselect_b32 s50, 0, 0x48
	s_cselect_b32 s52, 0, s3
	s_add_i32 s58, s72, 0x4000
	s_addk_i32 s72, 0x3000
	s_mov_b32 s90, 2
	s_branch .LBB0_731

.LBB0_730:
	s_or_b32 s20, s90, 1
	s_add_i32 s90, s90, 2
	s_mov_b32 s91, s21
	ds_read_b128 v[142:145], v137
	ds_read_b128 v[146:149], v137 offset:1024
	ds_read_b128 v[150:153], v137 offset:2048
	ds_read_b128 v[154:157], v137 offset:3072
	ds_read_b128 v[158:161], v138
	ds_read_b128 v[162:165], v138 offset:1024
	ds_read_b128 v[166:169], v138 offset:2048
	ds_read_b128 v[172:175], v138 offset:3072
	s_lshl_b64 s[96:97], s[20:21], 7
	s_lshl_b64 s[2:3], s[90:91], 7
	s_add_u32 s20, s78, s2
	s_addc_u32 s73, s79, s3
	s_and_b64 s[12:13], s[92:93], exec
	s_cselect_b32 s95, s73, s87
	s_cselect_b32 s94, s20, s86
	s_add_u32 s12, s76, s2
	s_addc_u32 s13, s77, s3
	s_and_b64 s[2:3], s[92:93], exec
	s_cselect_b32 s93, s13, s89
	s_cselect_b32 s92, s12, s88
	s_add_u32 s2, s94, 0x80
	s_addc_u32 s3, s95, 0
	s_add_u32 s12, s92, 0x80
	s_addc_u32 s13, s93, 0
	ds_read_b128 v[176:179], v136
	ds_read_b128 v[180:183], v136 offset:1024
	ds_read_b128 v[184:187], v136 offset:2048
	ds_read_b128 v[188:191], v136 offset:3072
	ds_read_b128 v[196:199], v136 offset:4096
	ds_read_b128 v[200:203], v136 offset:5120
	ds_read_b128 v[204:207], v136 offset:6144
	ds_read_b128 v[208:211], v136 offset:7168
	s_add_u32 s96, s59, s96
	s_addc_u32 s97, s38, s97
	s_add_i32 m0, s43, 0xc000
	s_nop 0
	global_load_lds_dwordx4 v134, s[96:97]
	s_nop 0
	s_add_i32 m0, s43, 0xe000
	s_nop 0
	global_load_lds_dwordx4 v135, s[96:97]
	s_waitcnt vmcnt(8)
	s_waitcnt lgkmcnt(0)
	s_setprio 1
	s_barrier
	v_mfma_f32_16x16x32_bf16 v[70:73], v[142:145], v[176:179], v[70:73]
	v_mfma_f32_16x16x32_bf16 v[86:89], v[150:153], v[176:179], v[86:89]
	s_waitcnt lgkmcnt(5)
	v_mfma_f32_16x16x32_bf16 v[74:77], v[142:145], v[184:187], v[74:77]
	v_mfma_f32_16x16x32_bf16 v[90:93], v[150:153], v[184:187], v[90:93]
	s_waitcnt lgkmcnt(3)
	v_mfma_f32_16x16x32_bf16 v[78:81], v[142:145], v[196:199], v[78:81]
	v_mfma_f32_16x16x32_bf16 v[94:97], v[150:153], v[196:199], v[94:97]
	s_waitcnt lgkmcnt(1)
	v_mfma_f32_16x16x32_bf16 v[82:85], v[142:145], v[204:207], v[82:85]
	v_mfma_f32_16x16x32_bf16 v[98:101], v[150:153], v[204:207], v[98:101]
	v_mfma_f32_16x16x32_bf16 v[70:73], v[146:149], v[180:183], v[70:73]
	v_mfma_f32_16x16x32_bf16 v[86:89], v[154:157], v[180:183], v[86:89]
	v_mfma_f32_16x16x32_bf16 v[74:77], v[146:149], v[188:191], v[74:77]
	v_mfma_f32_16x16x32_bf16 v[90:93], v[154:157], v[188:191], v[90:93]
	v_mfma_f32_16x16x32_bf16 v[78:81], v[146:149], v[200:203], v[78:81]
	v_mfma_f32_16x16x32_bf16 v[94:97], v[154:157], v[200:203], v[94:97]
	s_waitcnt lgkmcnt(0)
	v_mfma_f32_16x16x32_bf16 v[82:85], v[146:149], v[208:211], v[82:85]
	v_mfma_f32_16x16x32_bf16 v[98:101], v[154:157], v[208:211], v[98:101]
	s_setprio 0
	s_setprio 1
	v_mfma_f32_16x16x32_bf16 v[102:105], v[158:161], v[176:179], v[102:105]
	v_mfma_f32_16x16x32_bf16 v[118:121], v[166:169], v[176:179], v[118:121]
	v_mfma_f32_16x16x32_bf16 v[106:109], v[158:161], v[184:187], v[106:109]
	v_mfma_f32_16x16x32_bf16 v[122:125], v[166:169], v[184:187], v[122:125]
	v_mfma_f32_16x16x32_bf16 v[110:113], v[158:161], v[196:199], v[110:113]
	v_mfma_f32_16x16x32_bf16 v[126:129], v[166:169], v[196:199], v[126:129]
	v_mfma_f32_16x16x32_bf16 v[114:117], v[158:161], v[204:207], v[114:117]
	v_mfma_f32_16x16x32_bf16 v[130:133], v[166:169], v[204:207], v[130:133]
	v_mfma_f32_16x16x32_bf16 v[102:105], v[162:165], v[180:183], v[102:105]
	v_mfma_f32_16x16x32_bf16 v[118:121], v[172:175], v[180:183], v[118:121]
	v_mfma_f32_16x16x32_bf16 v[106:109], v[162:165], v[188:191], v[106:109]
	v_mfma_f32_16x16x32_bf16 v[122:125], v[172:175], v[188:191], v[122:125]
	v_mfma_f32_16x16x32_bf16 v[110:113], v[162:165], v[200:203], v[110:113]
	v_mfma_f32_16x16x32_bf16 v[126:129], v[172:175], v[200:203], v[126:129]
	v_mfma_f32_16x16x32_bf16 v[114:117], v[162:165], v[208:211], v[114:117]
	v_mfma_f32_16x16x32_bf16 v[130:133], v[172:175], v[208:211], v[130:133]
	s_barrier
	s_setprio 0
	ds_read_b128 v[176:179], v136 offset:16384
	ds_read_b128 v[180:183], v136 offset:17408
	ds_read_b128 v[184:187], v136 offset:18432
	ds_read_b128 v[188:191], v136 offset:19456
	ds_read_b128 v[196:199], v136 offset:20480
	ds_read_b128 v[200:203], v136 offset:21504
	ds_read_b128 v[204:207], v136 offset:22528
	ds_read_b128 v[208:211], v136 offset:23552
	s_add_i32 m0, s43, 0x10000
	s_nop 0
	global_load_lds_dwordx4 v134, s[92:93]
	s_nop 0
	s_add_i32 m0, s43, 0x12000
	s_nop 0
	global_load_lds_dwordx4 v135, s[92:93]
	s_add_u32 s92, s92, s16
	s_addc_u32 s93, s93, 0
	s_add_i32 m0, s43, 0x14000
	s_nop 0
	global_load_lds_dwordx4 v134, s[92:93]
	s_nop 0
	s_add_i32 m0, s43, 0x16000
	s_nop 0
	global_load_lds_dwordx4 v135, s[92:93]
	s_nop 0
	s_add_i32 m0, s43, 0
	s_nop 0
	global_load_lds_dwordx4 v134, s[94:95]
	s_nop 0
	s_add_i32 m0, s43, 0x2000
	s_nop 0
	global_load_lds_dwordx4 v135, s[94:95]
	s_waitcnt vmcnt(8)
	s_waitcnt lgkmcnt(0)
	s_setprio 1
	s_barrier
	v_mfma_f32_16x16x32_bf16 v[4:7], v[142:145], v[176:179], v[6:9]
	v_mfma_f32_16x16x32_bf16 v[22:25], v[150:153], v[176:179], v[22:25]
	s_waitcnt lgkmcnt(5)
	v_mfma_f32_16x16x32_bf16 v[8:11], v[142:145], v[184:187], v[10:13]
	v_mfma_f32_16x16x32_bf16 v[26:29], v[150:153], v[184:187], v[26:29]
	s_waitcnt lgkmcnt(3)
	v_mfma_f32_16x16x32_bf16 v[14:17], v[142:145], v[196:199], v[14:17]
	v_mfma_f32_16x16x32_bf16 v[30:33], v[150:153], v[196:199], v[30:33]
	s_waitcnt lgkmcnt(1)
	v_mfma_f32_16x16x32_bf16 v[18:21], v[142:145], v[204:207], v[18:21]
	v_mfma_f32_16x16x32_bf16 v[34:37], v[150:153], v[204:207], v[34:37]
	v_mfma_f32_16x16x32_bf16 v[4:7], v[146:149], v[180:183], v[4:7]
	v_mfma_f32_16x16x32_bf16 v[22:25], v[154:157], v[180:183], v[22:25]
	v_mfma_f32_16x16x32_bf16 v[10:13], v[146:149], v[188:191], v[8:11]
	v_mfma_f32_16x16x32_bf16 v[26:29], v[154:157], v[188:191], v[26:29]
	v_mfma_f32_16x16x32_bf16 v[14:17], v[146:149], v[200:203], v[14:17]
	v_mfma_f32_16x16x32_bf16 v[30:33], v[154:157], v[200:203], v[30:33]
	s_waitcnt lgkmcnt(0)
	v_mfma_f32_16x16x32_bf16 v[18:21], v[146:149], v[208:211], v[18:21]
	v_mfma_f32_16x16x32_bf16 v[34:37], v[154:157], v[208:211], v[34:37]
	s_setprio 0
	s_setprio 1
	v_mfma_f32_16x16x32_bf16 v[38:41], v[158:161], v[176:179], v[38:41]
	v_mfma_f32_16x16x32_bf16 v[54:57], v[166:169], v[176:179], v[54:57]
	v_mfma_f32_16x16x32_bf16 v[42:45], v[158:161], v[184:187], v[42:45]
	v_mfma_f32_16x16x32_bf16 v[58:61], v[166:169], v[184:187], v[58:61]
	v_mfma_f32_16x16x32_bf16 v[46:49], v[158:161], v[196:199], v[46:49]
	v_mfma_f32_16x16x32_bf16 v[62:65], v[166:169], v[196:199], v[62:65]
	v_mfma_f32_16x16x32_bf16 v[50:53], v[158:161], v[204:207], v[50:53]
	v_mfma_f32_16x16x32_bf16 v[66:69], v[166:169], v[204:207], v[66:69]
	v_mfma_f32_16x16x32_bf16 v[38:41], v[162:165], v[180:183], v[38:41]
	v_mfma_f32_16x16x32_bf16 v[54:57], v[172:175], v[180:183], v[54:57]
	v_mfma_f32_16x16x32_bf16 v[42:45], v[162:165], v[188:191], v[42:45]
	v_mfma_f32_16x16x32_bf16 v[58:61], v[172:175], v[188:191], v[58:61]
	v_mfma_f32_16x16x32_bf16 v[46:49], v[162:165], v[200:203], v[46:49]
	v_mfma_f32_16x16x32_bf16 v[62:65], v[172:175], v[200:203], v[62:65]
	v_mfma_f32_16x16x32_bf16 v[50:53], v[162:165], v[208:211], v[50:53]
	v_mfma_f32_16x16x32_bf16 v[66:69], v[172:175], v[208:211], v[66:69]
	s_barrier
	s_setprio 0
	ds_read_b128 v[142:145], v139
	ds_read_b128 v[146:149], v139 offset:1024
	ds_read_b128 v[150:153], v139 offset:2048
	ds_read_b128 v[154:157], v139 offset:3072
	ds_read_b128 v[158:161], v140
	ds_read_b128 v[162:165], v140 offset:1024
	ds_read_b128 v[166:169], v140 offset:2048
	ds_read_b128 v[172:175], v140 offset:3072
	ds_read_b128 v[176:179], v136 offset:32768
	ds_read_b128 v[180:183], v136 offset:33792
	ds_read_b128 v[184:187], v136 offset:34816
	ds_read_b128 v[188:191], v136 offset:35840
	ds_read_b128 v[196:199], v136 offset:36864
	ds_read_b128 v[200:203], v136 offset:37888
	ds_read_b128 v[204:207], v136 offset:38912
	ds_read_b128 v[208:211], v136 offset:39936
	s_add_u32 s92, s94, s16
	s_addc_u32 s93, s95, 0
	s_add_i32 m0, s43, 0x4000
	s_nop 0
	global_load_lds_dwordx4 v134, s[92:93]
	s_nop 0
	s_add_i32 m0, s43, 0x6000
	s_nop 0
	global_load_lds_dwordx4 v135, s[92:93]
	s_waitcnt vmcnt(8)
	s_waitcnt lgkmcnt(0)
	s_setprio 1
	s_barrier
	v_mfma_f32_16x16x32_bf16 v[70:73], v[142:145], v[176:179], v[70:73]
	v_mfma_f32_16x16x32_bf16 v[86:89], v[150:153], v[176:179], v[86:89]
	s_waitcnt lgkmcnt(5)
	v_mfma_f32_16x16x32_bf16 v[74:77], v[142:145], v[184:187], v[74:77]
	v_mfma_f32_16x16x32_bf16 v[90:93], v[150:153], v[184:187], v[90:93]
	s_waitcnt lgkmcnt(3)
	v_mfma_f32_16x16x32_bf16 v[78:81], v[142:145], v[196:199], v[78:81]
	v_mfma_f32_16x16x32_bf16 v[94:97], v[150:153], v[196:199], v[94:97]
	s_waitcnt lgkmcnt(1)
	v_mfma_f32_16x16x32_bf16 v[82:85], v[142:145], v[204:207], v[82:85]
	v_mfma_f32_16x16x32_bf16 v[98:101], v[150:153], v[204:207], v[98:101]
	v_mfma_f32_16x16x32_bf16 v[70:73], v[146:149], v[180:183], v[70:73]
	v_mfma_f32_16x16x32_bf16 v[86:89], v[154:157], v[180:183], v[86:89]
	v_mfma_f32_16x16x32_bf16 v[74:77], v[146:149], v[188:191], v[74:77]
	v_mfma_f32_16x16x32_bf16 v[90:93], v[154:157], v[188:191], v[90:93]
	v_mfma_f32_16x16x32_bf16 v[78:81], v[146:149], v[200:203], v[78:81]
	v_mfma_f32_16x16x32_bf16 v[94:97], v[154:157], v[200:203], v[94:97]
	s_waitcnt lgkmcnt(0)
	v_mfma_f32_16x16x32_bf16 v[82:85], v[146:149], v[208:211], v[82:85]
	v_mfma_f32_16x16x32_bf16 v[98:101], v[154:157], v[208:211], v[98:101]
	s_setprio 0
	s_setprio 1
	v_mfma_f32_16x16x32_bf16 v[102:105], v[158:161], v[176:179], v[102:105]
	v_mfma_f32_16x16x32_bf16 v[118:121], v[166:169], v[176:179], v[118:121]
	v_mfma_f32_16x16x32_bf16 v[106:109], v[158:161], v[184:187], v[106:109]
	v_mfma_f32_16x16x32_bf16 v[122:125], v[166:169], v[184:187], v[122:125]
	v_mfma_f32_16x16x32_bf16 v[110:113], v[158:161], v[196:199], v[110:113]
	v_mfma_f32_16x16x32_bf16 v[126:129], v[166:169], v[196:199], v[126:129]
	v_mfma_f32_16x16x32_bf16 v[114:117], v[158:161], v[204:207], v[114:117]
	v_mfma_f32_16x16x32_bf16 v[130:133], v[166:169], v[204:207], v[130:133]
	v_mfma_f32_16x16x32_bf16 v[102:105], v[162:165], v[180:183], v[102:105]
	v_mfma_f32_16x16x32_bf16 v[118:121], v[172:175], v[180:183], v[118:121]
	v_mfma_f32_16x16x32_bf16 v[106:109], v[162:165], v[188:191], v[106:109]
	v_mfma_f32_16x16x32_bf16 v[122:125], v[172:175], v[188:191], v[122:125]
	v_mfma_f32_16x16x32_bf16 v[110:113], v[162:165], v[200:203], v[110:113]
	v_mfma_f32_16x16x32_bf16 v[126:129], v[172:175], v[200:203], v[126:129]
	v_mfma_f32_16x16x32_bf16 v[114:117], v[162:165], v[208:211], v[114:117]
	v_mfma_f32_16x16x32_bf16 v[130:133], v[172:175], v[208:211], v[130:133]
	s_barrier
	s_setprio 0
	ds_read_b128 v[176:179], v136 offset:49152
	ds_read_b128 v[180:183], v136 offset:50176
	ds_read_b128 v[184:187], v136 offset:51200
	ds_read_b128 v[188:191], v136 offset:52224
	ds_read_b128 v[196:199], v136 offset:53248
	ds_read_b128 v[200:203], v136 offset:54272
	ds_read_b128 v[204:207], v136 offset:55296
	ds_read_b128 v[208:211], v136 offset:56320
	s_add_i32 m0, s43, 0x18000
	s_nop 0
	global_load_lds_dwordx4 v134, s[12:13]
	s_nop 0
	s_add_i32 m0, s43, 0x1a000
	s_nop 0
	global_load_lds_dwordx4 v135, s[12:13]
	s_add_u32 s12, s12, s16
	s_addc_u32 s13, s13, 0
	s_add_i32 m0, s43, 0x1c000
	s_nop 0
	global_load_lds_dwordx4 v134, s[12:13]
	s_nop 0
	s_add_i32 m0, s43, 0x1e000
	s_nop 0
	global_load_lds_dwordx4 v135, s[12:13]
	s_nop 0
	s_add_i32 m0, s43, 0x8000
	s_nop 0
	global_load_lds_dwordx4 v134, s[2:3]
	s_nop 0
	s_add_i32 m0, s43, 0xa000
	s_nop 0
	global_load_lds_dwordx4 v135, s[2:3]
	s_waitcnt vmcnt(8)
	s_waitcnt lgkmcnt(0)
	s_setprio 1
	s_barrier
	v_mfma_f32_16x16x32_bf16 v[4:7], v[142:145], v[176:179], v[4:7]
	v_mfma_f32_16x16x32_bf16 v[22:25], v[150:153], v[176:179], v[22:25]
	s_waitcnt lgkmcnt(5)
	v_mfma_f32_16x16x32_bf16 v[10:13], v[142:145], v[184:187], v[10:13]
	v_mfma_f32_16x16x32_bf16 v[26:29], v[150:153], v[184:187], v[26:29]
	s_waitcnt lgkmcnt(3)
	v_mfma_f32_16x16x32_bf16 v[14:17], v[142:145], v[196:199], v[14:17]
	v_mfma_f32_16x16x32_bf16 v[30:33], v[150:153], v[196:199], v[30:33]
	s_waitcnt lgkmcnt(1)
	v_mfma_f32_16x16x32_bf16 v[18:21], v[142:145], v[204:207], v[18:21]
	v_mfma_f32_16x16x32_bf16 v[34:37], v[150:153], v[204:207], v[34:37]
	v_mfma_f32_16x16x32_bf16 v[6:9], v[146:149], v[180:183], v[4:7]
	v_mfma_f32_16x16x32_bf16 v[22:25], v[154:157], v[180:183], v[22:25]
	v_mfma_f32_16x16x32_bf16 v[10:13], v[146:149], v[188:191], v[10:13]
	v_mfma_f32_16x16x32_bf16 v[26:29], v[154:157], v[188:191], v[26:29]
	v_mfma_f32_16x16x32_bf16 v[14:17], v[146:149], v[200:203], v[14:17]
	v_mfma_f32_16x16x32_bf16 v[30:33], v[154:157], v[200:203], v[30:33]
	s_waitcnt lgkmcnt(0)
	v_mfma_f32_16x16x32_bf16 v[18:21], v[146:149], v[208:211], v[18:21]
	v_mfma_f32_16x16x32_bf16 v[34:37], v[154:157], v[208:211], v[34:37]
	s_setprio 0
	s_setprio 1
	v_mfma_f32_16x16x32_bf16 v[38:41], v[158:161], v[176:179], v[38:41]
	v_mfma_f32_16x16x32_bf16 v[54:57], v[166:169], v[176:179], v[54:57]
	v_mfma_f32_16x16x32_bf16 v[42:45], v[158:161], v[184:187], v[42:45]
	v_mfma_f32_16x16x32_bf16 v[58:61], v[166:169], v[184:187], v[58:61]
	v_mfma_f32_16x16x32_bf16 v[46:49], v[158:161], v[196:199], v[46:49]
	v_mfma_f32_16x16x32_bf16 v[62:65], v[166:169], v[196:199], v[62:65]
	v_mfma_f32_16x16x32_bf16 v[50:53], v[158:161], v[204:207], v[50:53]
	v_mfma_f32_16x16x32_bf16 v[66:69], v[166:169], v[204:207], v[66:69]
	v_mfma_f32_16x16x32_bf16 v[38:41], v[162:165], v[180:183], v[38:41]
	v_mfma_f32_16x16x32_bf16 v[54:57], v[172:175], v[180:183], v[54:57]
	v_mfma_f32_16x16x32_bf16 v[42:45], v[162:165], v[188:191], v[42:45]
	v_mfma_f32_16x16x32_bf16 v[58:61], v[172:175], v[188:191], v[58:61]
	v_mfma_f32_16x16x32_bf16 v[46:49], v[162:165], v[200:203], v[46:49]
	v_mfma_f32_16x16x32_bf16 v[62:65], v[172:175], v[200:203], v[62:65]
	v_mfma_f32_16x16x32_bf16 v[50:53], v[162:165], v[208:211], v[50:53]
	v_mfma_f32_16x16x32_bf16 v[66:69], v[172:175], v[208:211], v[66:69]
	s_barrier
	s_setprio 0
	s_cmp_ge_u32 s90, s55
	s_cbranch_scc1 .LBB0_848

.LBB0_1071:
	s_add_i32 s16, s38, 1
	s_add_i32 s3, s16, s35
	s_mul_i32 s3, s3, s23
	s_add_i32 s3, s3, s22
	s_add_i32 s12, s18, s3
	s_cmp_lt_i32 s12, s2
	s_cselect_b64 s[78:79], -1, 0
	s_cmp_ge_i32 s12, s2
	s_cselect_b64 s[74:75], -1, 0
	s_lshr_b32 s2, s2, 1
	s_cmp_lt_i32 s12, s2
	s_cselect_b32 s2, 0, s2
	s_cselect_b32 s13, 0, 4
	s_sub_i32 s2, s12, s2
	s_and_b32 s3, s3, 3
	s_ashr_i32 s37, s2, 2
	s_or_b32 s2, s3, s13
	s_or_b32 s53, s2, s28
	s_and_b64 s[2:3], s[78:79], exec
	s_cselect_b32 s82, s53, s7
	s_cselect_b32 s2, s37, s6
	s_ashr_i32 s83, s82, 31
	s_lshl_b64 s[6:7], s[82:83], 19
	s_add_u32 s76, s51, s6
	s_addc_u32 s77, s97, s7
	s_ashr_i32 s3, s2, 31
	s_lshl_b64 s[2:3], s[2:3], 19
	s_add_u32 s80, s56, s2
	s_addc_u32 s81, s96, s3
	s_add_u32 s12, s62, 0x100
	s_addc_u32 s13, s63, 0
	v_add_u32_e32 v134, 0x10000, v151
	v_add_u32_e32 v135, 0x14000, v151
	s_add_u32 s2, s62, 0x180
	ds_read_b128 v[4:7], v134
	ds_read_b128 v[8:11], v134 offset:1024
	ds_read_b128 v[12:15], v134 offset:2048
	ds_read_b128 v[16:19], v134 offset:3072
	ds_read_b128 v[20:23], v135
	ds_read_b128 v[24:27], v135 offset:1024
	ds_read_b128 v[28:31], v135 offset:2048
	ds_read_b128 v[32:35], v135 offset:3072
	s_addc_u32 s3, s63, 0
	s_and_b64 s[6:7], s[78:79], exec
	s_cselect_b32 s33, s77, s63
	s_cselect_b32 s39, s76, s62
	s_add_u32 s6, s64, 0x100
	s_addc_u32 s7, s65, 0
	s_and_b64 s[26:27], s[78:79], exec
	s_mov_b32 s29, 2
	s_cselect_b32 s54, s81, s65
	s_cselect_b32 s47, s80, s64
	ds_read_b128 v[36:39], v152
	ds_read_b128 v[40:43], v152 offset:1024
	ds_read_b128 v[44:47], v152 offset:2048
	ds_read_b128 v[48:51], v152 offset:3072
	ds_read_b128 v[52:55], v152 offset:4096
	ds_read_b128 v[56:59], v152 offset:5120
	ds_read_b128 v[60:63], v152 offset:6144
	ds_read_b128 v[64:67], v152 offset:7168
	s_add_u32 s26, s62, 0x40080
	s_addc_u32 s27, s63, 0
	s_add_i32 m0, s69, 0xc000
	s_nop 0
	global_load_lds_dwordx4 v147, s[26:27]
	s_nop 0
	s_add_i32 m0, s69, 0xe000
	s_nop 0
	global_load_lds_dwordx4 v148, s[26:27]
	s_waitcnt vmcnt(8)
	s_waitcnt lgkmcnt(0)
	s_setprio 1
	s_barrier
	v_mfma_f32_16x16x32_bf16 v[92:95], v[4:7], v[60:63], 0
	v_mfma_f32_16x16x32_bf16 v[68:71], v[4:7], v[36:39], 0
	v_mfma_f32_16x16x32_bf16 v[72:75], v[12:15], v[36:39], 0
	v_mfma_f32_16x16x32_bf16 v[76:79], v[4:7], v[44:47], 0
	v_mfma_f32_16x16x32_bf16 v[80:83], v[12:15], v[44:47], 0
	v_mfma_f32_16x16x32_bf16 v[84:87], v[4:7], v[52:55], 0
	v_mfma_f32_16x16x32_bf16 v[88:91], v[12:15], v[52:55], 0
	s_waitcnt lgkmcnt(0)
	v_mfma_f32_16x16x32_bf16 v[96:99], v[8:11], v[64:67], v[92:95]
	v_mfma_f32_16x16x32_bf16 v[92:95], v[12:15], v[60:63], 0
	v_mfma_f32_16x16x32_bf16 v[68:71], v[8:11], v[40:43], v[68:71]
	v_mfma_f32_16x16x32_bf16 v[72:75], v[16:19], v[40:43], v[72:75]
	v_mfma_f32_16x16x32_bf16 v[76:79], v[8:11], v[48:51], v[76:79]
	v_mfma_f32_16x16x32_bf16 v[80:83], v[16:19], v[48:51], v[80:83]
	v_mfma_f32_16x16x32_bf16 v[84:87], v[8:11], v[56:59], v[84:87]
	v_mfma_f32_16x16x32_bf16 v[88:91], v[16:19], v[56:59], v[88:91]
	v_mfma_f32_16x16x32_bf16 v[104:107], v[16:19], v[64:67], v[92:95]
	s_setprio 0
	s_setprio 1
	v_mfma_f32_16x16x32_bf16 v[92:95], v[20:23], v[36:39], 0
	v_mfma_f32_16x16x32_bf16 v[36:39], v[28:31], v[36:39], 0
	v_mfma_f32_16x16x32_bf16 v[112:115], v[24:27], v[40:43], v[92:95]
	v_mfma_f32_16x16x32_bf16 v[36:39], v[32:35], v[40:43], v[36:39]
	v_mfma_f32_16x16x32_bf16 v[40:43], v[20:23], v[44:47], 0
	v_mfma_f32_16x16x32_bf16 v[44:47], v[28:31], v[44:47], 0
	v_mfma_f32_16x16x32_bf16 v[40:43], v[24:27], v[48:51], v[40:43]
	v_mfma_f32_16x16x32_bf16 v[44:47], v[32:35], v[48:51], v[44:47]
	v_mfma_f32_16x16x32_bf16 v[48:51], v[20:23], v[52:55], 0
	v_mfma_f32_16x16x32_bf16 v[52:55], v[28:31], v[52:55], 0
	v_mfma_f32_16x16x32_bf16 v[48:51], v[24:27], v[56:59], v[48:51]
	v_mfma_f32_16x16x32_bf16 v[52:55], v[32:35], v[56:59], v[52:55]
	v_mfma_f32_16x16x32_bf16 v[56:59], v[20:23], v[60:63], 0
	v_mfma_f32_16x16x32_bf16 v[60:63], v[28:31], v[60:63], 0
	v_mfma_f32_16x16x32_bf16 v[56:59], v[24:27], v[64:67], v[56:59]
	v_mfma_f32_16x16x32_bf16 v[60:63], v[32:35], v[64:67], v[60:63]
	s_barrier
	s_setprio 0
	ds_read_b128 v[64:67], v152 offset:16384
	ds_read_b128 v[92:95], v152 offset:17408
	ds_read_b128 v[100:103], v152 offset:18432
	ds_read_b128 v[108:111], v152 offset:19456
	ds_read_b128 v[116:119], v152 offset:20480
	ds_read_b128 v[120:123], v152 offset:21504
	ds_read_b128 v[124:127], v152 offset:22528
	ds_read_b128 v[128:131], v152 offset:23552
	s_add_i32 m0, s69, 0x10000
	s_nop 0
	global_load_lds_dwordx4 v1, s[6:7]
	s_nop 0
	s_add_i32 m0, s69, 0x12000
	s_nop 0
	global_load_lds_dwordx4 v146, s[6:7]
	s_add_u32 s6, s64, 0x40100
	s_addc_u32 s7, s65, 0
	s_add_i32 m0, s69, 0x14000
	s_nop 0
	global_load_lds_dwordx4 v1, s[6:7]
	s_nop 0
	s_add_i32 m0, s69, 0x16000
	s_nop 0
	global_load_lds_dwordx4 v146, s[6:7]
	s_nop 0
	s_add_i32 m0, s69, 0
	s_nop 0
	global_load_lds_dwordx4 v147, s[12:13]
	s_nop 0
	s_add_i32 m0, s69, 0x2000
	s_nop 0
	global_load_lds_dwordx4 v148, s[12:13]
	s_waitcnt vmcnt(8)
	s_waitcnt lgkmcnt(0)
	s_setprio 1
	s_barrier
	v_mfma_f32_16x16x32_bf16 v[136:139], v[4:7], v[64:67], 0
	s_waitcnt lgkmcnt(5)
	v_mfma_f32_16x16x32_bf16 v[154:157], v[4:7], v[100:103], 0
	s_waitcnt lgkmcnt(3)
	v_mfma_f32_16x16x32_bf16 v[162:165], v[4:7], v[116:119], 0
	s_waitcnt lgkmcnt(1)
	v_mfma_f32_16x16x32_bf16 v[4:7], v[4:7], v[124:127], 0
	v_mfma_f32_16x16x32_bf16 v[138:141], v[8:11], v[92:95], v[136:139]
	v_mfma_f32_16x16x32_bf16 v[154:157], v[8:11], v[108:111], v[154:157]
	v_mfma_f32_16x16x32_bf16 v[162:165], v[8:11], v[120:123], v[162:165]
	s_waitcnt lgkmcnt(0)
	v_mfma_f32_16x16x32_bf16 v[4:7], v[8:11], v[128:131], v[4:7]
	v_mfma_f32_16x16x32_bf16 v[8:11], v[12:15], v[124:127], 0
	v_mfma_f32_16x16x32_bf16 v[142:145], v[12:15], v[64:67], 0
	v_mfma_f32_16x16x32_bf16 v[158:161], v[12:15], v[100:103], 0
	v_mfma_f32_16x16x32_bf16 v[166:169], v[12:15], v[116:119], 0
	v_mfma_f32_16x16x32_bf16 v[8:11], v[16:19], v[128:131], v[8:11]
	v_mfma_f32_16x16x32_bf16 v[142:145], v[16:19], v[92:95], v[142:145]
	v_mfma_f32_16x16x32_bf16 v[158:161], v[16:19], v[108:111], v[158:161]
	v_mfma_f32_16x16x32_bf16 v[166:169], v[16:19], v[120:123], v[166:169]
	s_setprio 0
	s_setprio 1
	v_mfma_f32_16x16x32_bf16 v[12:15], v[20:23], v[64:67], 0
	v_mfma_f32_16x16x32_bf16 v[16:19], v[24:27], v[92:95], v[12:15]
	v_mfma_f32_16x16x32_bf16 v[12:15], v[28:31], v[64:67], 0
	v_mfma_f32_16x16x32_bf16 v[172:175], v[32:35], v[92:95], v[12:15]
	v_mfma_f32_16x16x32_bf16 v[12:15], v[20:23], v[100:103], 0
	v_mfma_f32_16x16x32_bf16 v[176:179], v[24:27], v[108:111], v[12:15]
	v_mfma_f32_16x16x32_bf16 v[12:15], v[28:31], v[100:103], 0
	v_mfma_f32_16x16x32_bf16 v[180:183], v[32:35], v[108:111], v[12:15]
	v_mfma_f32_16x16x32_bf16 v[12:15], v[20:23], v[116:119], 0
	v_mfma_f32_16x16x32_bf16 v[184:187], v[24:27], v[120:123], v[12:15]
	v_mfma_f32_16x16x32_bf16 v[12:15], v[28:31], v[116:119], 0
	v_mfma_f32_16x16x32_bf16 v[204:207], v[32:35], v[120:123], v[12:15]
	v_mfma_f32_16x16x32_bf16 v[12:15], v[20:23], v[124:127], 0
	v_mfma_f32_16x16x32_bf16 v[208:211], v[24:27], v[128:131], v[12:15]
	v_mfma_f32_16x16x32_bf16 v[12:15], v[28:31], v[124:127], 0
	v_mfma_f32_16x16x32_bf16 v[212:215], v[32:35], v[128:131], v[12:15]
	s_barrier
	s_setprio 0
	v_add_u32_e32 v136, 0x18000, v151
	v_add_u32_e32 v137, 0x1c000, v151
	s_nop 2
	ds_read_b128 v[12:15], v136
	ds_read_b128 v[24:27], v136 offset:1024
	ds_read_b128 v[32:35], v136 offset:2048
	ds_read_b128 v[216:219], v136 offset:3072
	ds_read_b128 v[220:223], v137
	ds_read_b128 v[224:227], v137 offset:1024
	ds_read_b128 v[228:231], v137 offset:2048
	ds_read_b128 v[232:235], v137 offset:3072
	ds_read_b128 v[20:23], v152 offset:32768
	ds_read_b128 v[28:31], v152 offset:33792
	ds_read_b128 v[236:239], v152 offset:34816
	ds_read_b128 v[240:243], v152 offset:35840
	ds_read_b128 v[244:247], v152 offset:36864
	ds_read_b128 v[248:251], v152 offset:37888
	ds_read_b128 v[200:203], v152 offset:38912
	ds_read_b128 v[196:199], v152 offset:39936
	s_add_u32 s6, s62, 0x40100
	s_addc_u32 s7, s63, 0
	s_add_i32 m0, s69, 0x4000
	s_nop 0
	global_load_lds_dwordx4 v147, s[6:7]
	s_nop 0
	s_add_i32 m0, s69, 0x6000
	s_nop 0
	global_load_lds_dwordx4 v148, s[6:7]
	s_waitcnt vmcnt(8)
	s_waitcnt lgkmcnt(0)
	s_setprio 1
	s_barrier
	v_mfma_f32_16x16x32_bf16 v[64:67], v[12:15], v[20:23], v[68:71]
	s_waitcnt lgkmcnt(6)
	v_mfma_f32_16x16x32_bf16 v[124:127], v[24:27], v[28:31], v[64:67]
	v_mfma_f32_16x16x32_bf16 v[64:67], v[32:35], v[20:23], v[72:75]
	v_mfma_f32_16x16x32_bf16 v[116:119], v[216:219], v[28:31], v[64:67]
	s_waitcnt lgkmcnt(5)
	v_mfma_f32_16x16x32_bf16 v[64:67], v[12:15], v[236:239], v[76:79]
	s_waitcnt lgkmcnt(4)
	v_mfma_f32_16x16x32_bf16 v[108:111], v[24:27], v[240:243], v[64:67]
	v_mfma_f32_16x16x32_bf16 v[64:67], v[32:35], v[236:239], v[80:83]
	v_mfma_f32_16x16x32_bf16 v[100:103], v[216:219], v[240:243], v[64:67]
	s_waitcnt lgkmcnt(3)
	v_mfma_f32_16x16x32_bf16 v[64:67], v[12:15], v[244:247], v[84:87]
	s_waitcnt lgkmcnt(2)
	v_mfma_f32_16x16x32_bf16 v[92:95], v[24:27], v[248:251], v[64:67]
	v_mfma_f32_16x16x32_bf16 v[64:67], v[32:35], v[244:247], v[88:91]
	v_mfma_f32_16x16x32_bf16 v[84:87], v[216:219], v[248:251], v[64:67]
	s_waitcnt lgkmcnt(1)
	v_mfma_f32_16x16x32_bf16 v[64:67], v[12:15], v[200:203], v[96:99]
	s_waitcnt lgkmcnt(0)
	v_mfma_f32_16x16x32_bf16 v[76:79], v[24:27], v[196:199], v[64:67]
	v_mfma_f32_16x16x32_bf16 v[64:67], v[32:35], v[200:203], v[104:107]
	v_mfma_f32_16x16x32_bf16 v[64:67], v[216:219], v[196:199], v[64:67]
	s_setprio 0
	s_setprio 1
	v_mfma_f32_16x16x32_bf16 v[68:71], v[220:223], v[20:23], v[112:115]
	v_mfma_f32_16x16x32_bf16 v[20:23], v[228:231], v[20:23], v[36:39]
	v_mfma_f32_16x16x32_bf16 v[120:123], v[232:235], v[28:31], v[20:23]
	v_mfma_f32_16x16x32_bf16 v[20:23], v[220:223], v[236:239], v[40:43]
	v_mfma_f32_16x16x32_bf16 v[112:115], v[224:227], v[240:243], v[20:23]
	v_mfma_f32_16x16x32_bf16 v[20:23], v[228:231], v[236:239], v[44:47]
	v_mfma_f32_16x16x32_bf16 v[104:107], v[232:235], v[240:243], v[20:23]
	v_mfma_f32_16x16x32_bf16 v[20:23], v[220:223], v[244:247], v[48:51]
	v_mfma_f32_16x16x32_bf16 v[96:99], v[224:227], v[248:251], v[20:23]
	v_mfma_f32_16x16x32_bf16 v[20:23], v[228:231], v[244:247], v[52:55]
	v_mfma_f32_16x16x32_bf16 v[88:91], v[232:235], v[248:251], v[20:23]
	v_mfma_f32_16x16x32_bf16 v[20:23], v[220:223], v[200:203], v[56:59]
	v_mfma_f32_16x16x32_bf16 v[80:83], v[224:227], v[196:199], v[20:23]
	v_mfma_f32_16x16x32_bf16 v[20:23], v[228:231], v[200:203], v[60:63]
	v_mfma_f32_16x16x32_bf16 v[128:131], v[224:227], v[28:31], v[68:71]
	v_mfma_f32_16x16x32_bf16 v[72:75], v[232:235], v[196:199], v[20:23]
	s_barrier
	s_setprio 0
	s_add_u32 s6, s64, 0x180
	ds_read_b128 v[40:43], v152 offset:49152
	ds_read_b128 v[48:51], v152 offset:50176
	ds_read_b128 v[196:199], v152 offset:51200
	ds_read_b128 v[200:203], v152 offset:52224
	ds_read_b128 v[236:239], v152 offset:53248
	ds_read_b128 v[240:243], v152 offset:54272
	ds_read_b128 v[244:247], v152 offset:55296
	ds_read_b128 v[248:251], v152 offset:56320
	s_addc_u32 s7, s65, 0
	s_add_i32 m0, s69, 0x18000
	s_nop 0
	global_load_lds_dwordx4 v1, s[6:7]
	s_nop 0
	s_add_i32 m0, s69, 0x1a000
	s_nop 0
	global_load_lds_dwordx4 v146, s[6:7]
	s_add_u32 s6, s64, 0x40180
	s_addc_u32 s7, s65, 0
	s_add_i32 m0, s69, 0x1c000
	s_nop 0
	global_load_lds_dwordx4 v1, s[6:7]
	s_nop 0
	s_add_i32 m0, s69, 0x1e000
	s_nop 0
	global_load_lds_dwordx4 v146, s[6:7]
	s_nop 0
	s_add_i32 m0, s69, 0x8000
	s_nop 0
	global_load_lds_dwordx4 v147, s[2:3]
	s_nop 0
	s_add_i32 m0, s69, 0xa000
	s_nop 0
	global_load_lds_dwordx4 v148, s[2:3]
	s_waitcnt vmcnt(8)
	s_waitcnt lgkmcnt(0)
	s_setprio 1
	s_barrier
	v_mfma_f32_16x16x32_bf16 v[20:23], v[12:15], v[40:43], v[138:141]
	s_waitcnt lgkmcnt(6)
	v_mfma_f32_16x16x32_bf16 v[60:63], v[24:27], v[48:51], v[20:23]
	v_mfma_f32_16x16x32_bf16 v[20:23], v[32:35], v[40:43], v[142:145]
	v_mfma_f32_16x16x32_bf16 v[52:55], v[216:219], v[48:51], v[20:23]
	s_waitcnt lgkmcnt(5)
	v_mfma_f32_16x16x32_bf16 v[20:23], v[12:15], v[196:199], v[154:157]
	s_waitcnt lgkmcnt(4)
	v_mfma_f32_16x16x32_bf16 v[44:47], v[24:27], v[200:203], v[20:23]
	v_mfma_f32_16x16x32_bf16 v[20:23], v[32:35], v[196:199], v[158:161]
	v_mfma_f32_16x16x32_bf16 v[36:39], v[216:219], v[200:203], v[20:23]
	s_waitcnt lgkmcnt(3)
	v_mfma_f32_16x16x32_bf16 v[20:23], v[12:15], v[236:239], v[162:165]
	s_waitcnt lgkmcnt(1)
	v_mfma_f32_16x16x32_bf16 v[4:7], v[12:15], v[244:247], v[4:7]
	v_mfma_f32_16x16x32_bf16 v[28:31], v[24:27], v[240:243], v[20:23]
	v_mfma_f32_16x16x32_bf16 v[20:23], v[32:35], v[236:239], v[166:169]
	s_waitcnt lgkmcnt(0)
	v_mfma_f32_16x16x32_bf16 v[12:15], v[24:27], v[248:251], v[4:7]
	v_mfma_f32_16x16x32_bf16 v[4:7], v[32:35], v[244:247], v[8:11]
	v_mfma_f32_16x16x32_bf16 v[20:23], v[216:219], v[240:243], v[20:23]
	v_mfma_f32_16x16x32_bf16 v[4:7], v[216:219], v[248:251], v[4:7]
	s_setprio 0
	s_setprio 1
	v_mfma_f32_16x16x32_bf16 v[8:11], v[220:223], v[40:43], v[16:19]
	v_mfma_f32_16x16x32_bf16 v[68:71], v[224:227], v[48:51], v[8:11]
	v_mfma_f32_16x16x32_bf16 v[8:11], v[228:231], v[40:43], v[172:175]
	v_mfma_f32_16x16x32_bf16 v[56:59], v[232:235], v[48:51], v[8:11]
	v_mfma_f32_16x16x32_bf16 v[8:11], v[220:223], v[196:199], v[176:179]
	v_mfma_f32_16x16x32_bf16 v[48:51], v[224:227], v[200:203], v[8:11]
	v_mfma_f32_16x16x32_bf16 v[8:11], v[228:231], v[196:199], v[180:183]
	v_mfma_f32_16x16x32_bf16 v[40:43], v[232:235], v[200:203], v[8:11]
	v_mfma_f32_16x16x32_bf16 v[8:11], v[220:223], v[236:239], v[184:187]
	v_mfma_f32_16x16x32_bf16 v[32:35], v[224:227], v[240:243], v[8:11]
	v_mfma_f32_16x16x32_bf16 v[8:11], v[228:231], v[236:239], v[204:207]
	v_mfma_f32_16x16x32_bf16 v[24:27], v[232:235], v[240:243], v[8:11]
	v_mfma_f32_16x16x32_bf16 v[8:11], v[220:223], v[244:247], v[208:211]
	v_mfma_f32_16x16x32_bf16 v[16:19], v[224:227], v[248:251], v[8:11]
	v_mfma_f32_16x16x32_bf16 v[8:11], v[228:231], v[244:247], v[212:215]
	v_mfma_f32_16x16x32_bf16 v[8:11], v[232:235], v[248:251], v[8:11]
	s_barrier
	s_setprio 0
	s_add_i32 s2, s82, 1
	s_lshl_b32 s58, s82, 6
	s_and_b32 s3, s2, 31
	s_lshl_b32 s2, s2, 6
	s_add_i32 s59, s58, 0x9000
	s_add_i32 s52, s58, 0x8000
	s_add_i32 s40, s58, 0x7000
	s_addk_i32 s2, 0x6000
	s_cmp_eq_u32 s3, 0
	s_cselect_b32 s41, 0, 32
	s_cselect_b32 s50, 0, s2
	s_add_i32 s18, s58, 0x6000
	s_add_i32 s26, s58, 0x5000
	s_and_b32 s2, s82, 31
	s_add_i32 s3, s58, 0x4fc0
	s_cmp_eq_u32 s2, 0
	s_cselect_b32 s27, 0, 0x48
	s_cselect_b32 s6, 0, s3
	s_add_i32 s7, s58, 0x4000
	s_addk_i32 s58, 0x3000
	s_lshl_b64 s[2:3], s[82:83], 14
	s_add_u32 s84, s20, s2
	s_addc_u32 s85, s36, s3
	s_lshl_b32 s2, s82, 8
	s_and_b32 s2, s2, 0x400
	s_add_i32 s83, s2, 0
	s_add_i32 s83, s83, 0x24400

.LBB0_1192:
	s_lshl_b32 s12, s29, 7
	s_add_u32 s90, s62, s12
	s_addc_u32 s91, s63, 0
	s_add_u32 s13, s90, 0x100
	ds_read_b128 v[138:141], v134
	ds_read_b128 v[142:145], v134 offset:1024
	ds_read_b128 v[154:157], v134 offset:2048
	ds_read_b128 v[158:161], v134 offset:3072
	ds_read_b128 v[162:165], v135
	ds_read_b128 v[166:169], v135 offset:1024
	ds_read_b128 v[172:175], v135 offset:2048
	ds_read_b128 v[176:179], v135 offset:3072
	s_addc_u32 s88, s91, 0
	s_and_b64 s[2:3], s[86:87], exec
	s_cselect_b32 s89, s33, s88
	s_cselect_b32 s88, s39, s13
	s_add_u32 s2, s64, s12
	s_addc_u32 s3, s65, 0
	s_add_u32 s12, s2, 0x100
	s_addc_u32 s13, s3, 0
	s_and_b64 s[2:3], s[86:87], exec
	s_cselect_b32 s3, s54, s13
	s_cselect_b32 s2, s47, s12
	s_add_u32 s12, s88, 0x80
	s_addc_u32 s13, s89, 0
	s_add_u32 s86, s2, 0x80
	s_addc_u32 s87, s3, 0
	ds_read_b128 v[180:183], v152
	ds_read_b128 v[184:187], v152 offset:1024
	ds_read_b128 v[196:199], v152 offset:2048
	ds_read_b128 v[200:203], v152 offset:3072
	ds_read_b128 v[204:207], v152 offset:4096
	ds_read_b128 v[208:211], v152 offset:5120
	ds_read_b128 v[212:215], v152 offset:6144
	ds_read_b128 v[216:219], v152 offset:7168
	s_add_u32 s90, s90, 0x40080
	s_addc_u32 s91, s91, 0
	s_add_i32 m0, s69, 0xc000
	s_nop 0
	global_load_lds_dwordx4 v147, s[90:91]
	s_nop 0
	s_add_i32 m0, s69, 0xe000
	s_nop 0
	global_load_lds_dwordx4 v148, s[90:91]
	s_waitcnt vmcnt(8)
	s_waitcnt lgkmcnt(0)
	s_setprio 1
	s_barrier
	v_mfma_f32_16x16x32_bf16 v[124:127], v[138:141], v[180:183], v[124:127]
	v_mfma_f32_16x16x32_bf16 v[116:119], v[154:157], v[180:183], v[116:119]
	s_waitcnt lgkmcnt(5)
	v_mfma_f32_16x16x32_bf16 v[108:111], v[138:141], v[196:199], v[108:111]
	v_mfma_f32_16x16x32_bf16 v[100:103], v[154:157], v[196:199], v[100:103]
	s_waitcnt lgkmcnt(3)
	v_mfma_f32_16x16x32_bf16 v[92:95], v[138:141], v[204:207], v[92:95]
	v_mfma_f32_16x16x32_bf16 v[84:87], v[154:157], v[204:207], v[84:87]
	s_waitcnt lgkmcnt(1)
	v_mfma_f32_16x16x32_bf16 v[76:79], v[138:141], v[212:215], v[76:79]
	v_mfma_f32_16x16x32_bf16 v[64:67], v[154:157], v[212:215], v[64:67]
	v_mfma_f32_16x16x32_bf16 v[124:127], v[142:145], v[184:187], v[124:127]
	v_mfma_f32_16x16x32_bf16 v[116:119], v[158:161], v[184:187], v[116:119]
	v_mfma_f32_16x16x32_bf16 v[108:111], v[142:145], v[200:203], v[108:111]
	v_mfma_f32_16x16x32_bf16 v[100:103], v[158:161], v[200:203], v[100:103]
	v_mfma_f32_16x16x32_bf16 v[92:95], v[142:145], v[208:211], v[92:95]
	v_mfma_f32_16x16x32_bf16 v[84:87], v[158:161], v[208:211], v[84:87]
	s_waitcnt lgkmcnt(0)
	v_mfma_f32_16x16x32_bf16 v[76:79], v[142:145], v[216:219], v[76:79]
	v_mfma_f32_16x16x32_bf16 v[64:67], v[158:161], v[216:219], v[64:67]
	s_setprio 0
	s_setprio 1
	v_mfma_f32_16x16x32_bf16 v[128:131], v[162:165], v[180:183], v[128:131]
	v_mfma_f32_16x16x32_bf16 v[120:123], v[172:175], v[180:183], v[120:123]
	v_mfma_f32_16x16x32_bf16 v[112:115], v[162:165], v[196:199], v[112:115]
	v_mfma_f32_16x16x32_bf16 v[104:107], v[172:175], v[196:199], v[104:107]
	v_mfma_f32_16x16x32_bf16 v[96:99], v[162:165], v[204:207], v[96:99]
	v_mfma_f32_16x16x32_bf16 v[88:91], v[172:175], v[204:207], v[88:91]
	v_mfma_f32_16x16x32_bf16 v[80:83], v[162:165], v[212:215], v[80:83]
	v_mfma_f32_16x16x32_bf16 v[72:75], v[172:175], v[212:215], v[72:75]
	v_mfma_f32_16x16x32_bf16 v[128:131], v[166:169], v[184:187], v[128:131]
	v_mfma_f32_16x16x32_bf16 v[120:123], v[176:179], v[184:187], v[120:123]
	v_mfma_f32_16x16x32_bf16 v[112:115], v[166:169], v[200:203], v[112:115]
	v_mfma_f32_16x16x32_bf16 v[104:107], v[176:179], v[200:203], v[104:107]
	v_mfma_f32_16x16x32_bf16 v[96:99], v[166:169], v[208:211], v[96:99]
	v_mfma_f32_16x16x32_bf16 v[88:91], v[176:179], v[208:211], v[88:91]
	v_mfma_f32_16x16x32_bf16 v[80:83], v[166:169], v[216:219], v[80:83]
	v_mfma_f32_16x16x32_bf16 v[72:75], v[176:179], v[216:219], v[72:75]
	s_barrier
	s_setprio 0
	ds_read_b128 v[180:183], v152 offset:16384
	ds_read_b128 v[184:187], v152 offset:17408
	ds_read_b128 v[196:199], v152 offset:18432
	ds_read_b128 v[200:203], v152 offset:19456
	ds_read_b128 v[204:207], v152 offset:20480
	ds_read_b128 v[208:211], v152 offset:21504
	ds_read_b128 v[212:215], v152 offset:22528
	ds_read_b128 v[216:219], v152 offset:23552
	s_add_i32 m0, s69, 0x10000
	s_nop 0
	global_load_lds_dwordx4 v1, s[2:3]
	s_nop 0
	s_add_i32 m0, s69, 0x12000
	s_nop 0
	global_load_lds_dwordx4 v146, s[2:3]
	s_add_u32 s90, s2, 0x40000
	s_addc_u32 s91, s3, 0
	s_add_i32 m0, s69, 0x14000
	s_nop 0
	global_load_lds_dwordx4 v1, s[90:91]
	s_nop 0
	s_add_i32 m0, s69, 0x16000
	s_nop 0
	global_load_lds_dwordx4 v146, s[90:91]
	s_nop 0
	s_add_i32 m0, s69, 0
	s_nop 0
	global_load_lds_dwordx4 v147, s[88:89]
	s_nop 0
	s_add_i32 m0, s69, 0x2000
	s_nop 0
	global_load_lds_dwordx4 v148, s[88:89]
	s_waitcnt vmcnt(8)
	s_waitcnt lgkmcnt(0)
	s_setprio 1
	s_barrier
	v_mfma_f32_16x16x32_bf16 v[60:63], v[138:141], v[180:183], v[60:63]
	v_mfma_f32_16x16x32_bf16 v[52:55], v[154:157], v[180:183], v[52:55]
	s_waitcnt lgkmcnt(5)
	v_mfma_f32_16x16x32_bf16 v[44:47], v[138:141], v[196:199], v[44:47]
	v_mfma_f32_16x16x32_bf16 v[36:39], v[154:157], v[196:199], v[36:39]
	s_waitcnt lgkmcnt(3)
	v_mfma_f32_16x16x32_bf16 v[28:31], v[138:141], v[204:207], v[28:31]
	v_mfma_f32_16x16x32_bf16 v[20:23], v[154:157], v[204:207], v[20:23]
	s_waitcnt lgkmcnt(1)
	v_mfma_f32_16x16x32_bf16 v[12:15], v[138:141], v[212:215], v[12:15]
	v_mfma_f32_16x16x32_bf16 v[4:7], v[154:157], v[212:215], v[4:7]
	v_mfma_f32_16x16x32_bf16 v[60:63], v[142:145], v[184:187], v[60:63]
	v_mfma_f32_16x16x32_bf16 v[52:55], v[158:161], v[184:187], v[52:55]
	v_mfma_f32_16x16x32_bf16 v[44:47], v[142:145], v[200:203], v[44:47]
	v_mfma_f32_16x16x32_bf16 v[36:39], v[158:161], v[200:203], v[36:39]
	v_mfma_f32_16x16x32_bf16 v[28:31], v[142:145], v[208:211], v[28:31]
	v_mfma_f32_16x16x32_bf16 v[20:23], v[158:161], v[208:211], v[20:23]
	s_waitcnt lgkmcnt(0)
	v_mfma_f32_16x16x32_bf16 v[12:15], v[142:145], v[216:219], v[12:15]
	v_mfma_f32_16x16x32_bf16 v[4:7], v[158:161], v[216:219], v[4:7]
	s_setprio 0
	s_setprio 1
	v_mfma_f32_16x16x32_bf16 v[68:71], v[162:165], v[180:183], v[68:71]
	v_mfma_f32_16x16x32_bf16 v[56:59], v[172:175], v[180:183], v[56:59]
	v_mfma_f32_16x16x32_bf16 v[48:51], v[162:165], v[196:199], v[48:51]
	v_mfma_f32_16x16x32_bf16 v[40:43], v[172:175], v[196:199], v[40:43]
	v_mfma_f32_16x16x32_bf16 v[32:35], v[162:165], v[204:207], v[32:35]
	v_mfma_f32_16x16x32_bf16 v[24:27], v[172:175], v[204:207], v[24:27]
	v_mfma_f32_16x16x32_bf16 v[16:19], v[162:165], v[212:215], v[16:19]
	v_mfma_f32_16x16x32_bf16 v[8:11], v[172:175], v[212:215], v[8:11]
	v_mfma_f32_16x16x32_bf16 v[68:71], v[166:169], v[184:187], v[68:71]
	v_mfma_f32_16x16x32_bf16 v[56:59], v[176:179], v[184:187], v[56:59]
	v_mfma_f32_16x16x32_bf16 v[48:51], v[166:169], v[200:203], v[48:51]
	v_mfma_f32_16x16x32_bf16 v[40:43], v[176:179], v[200:203], v[40:43]
	v_mfma_f32_16x16x32_bf16 v[32:35], v[166:169], v[208:211], v[32:35]
	v_mfma_f32_16x16x32_bf16 v[24:27], v[176:179], v[208:211], v[24:27]
	v_mfma_f32_16x16x32_bf16 v[16:19], v[166:169], v[216:219], v[16:19]
	v_mfma_f32_16x16x32_bf16 v[8:11], v[176:179], v[216:219], v[8:11]
	s_barrier
	s_setprio 0
	ds_read_b128 v[138:141], v136
	ds_read_b128 v[142:145], v136 offset:1024
	ds_read_b128 v[154:157], v136 offset:2048
	ds_read_b128 v[158:161], v136 offset:3072
	ds_read_b128 v[162:165], v137
	ds_read_b128 v[166:169], v137 offset:1024
	ds_read_b128 v[172:175], v137 offset:2048
	ds_read_b128 v[176:179], v137 offset:3072
	ds_read_b128 v[180:183], v152 offset:32768
	ds_read_b128 v[184:187], v152 offset:33792
	ds_read_b128 v[196:199], v152 offset:34816
	ds_read_b128 v[200:203], v152 offset:35840
	ds_read_b128 v[204:207], v152 offset:36864
	ds_read_b128 v[208:211], v152 offset:37888
	ds_read_b128 v[212:215], v152 offset:38912
	ds_read_b128 v[216:219], v152 offset:39936
	s_add_u32 s88, s88, 0x40000
	s_addc_u32 s89, s89, 0
	s_add_i32 m0, s69, 0x4000
	s_nop 0
	global_load_lds_dwordx4 v147, s[88:89]
	s_nop 0
	s_add_i32 m0, s69, 0x6000
	s_nop 0
	global_load_lds_dwordx4 v148, s[88:89]
	s_waitcnt vmcnt(8)
	s_waitcnt lgkmcnt(0)
	s_setprio 1
	s_barrier
	v_mfma_f32_16x16x32_bf16 v[124:127], v[138:141], v[180:183], v[124:127]
	v_mfma_f32_16x16x32_bf16 v[116:119], v[154:157], v[180:183], v[116:119]
	s_waitcnt lgkmcnt(5)
	v_mfma_f32_16x16x32_bf16 v[108:111], v[138:141], v[196:199], v[108:111]
	v_mfma_f32_16x16x32_bf16 v[100:103], v[154:157], v[196:199], v[100:103]
	s_waitcnt lgkmcnt(3)
	v_mfma_f32_16x16x32_bf16 v[92:95], v[138:141], v[204:207], v[92:95]
	v_mfma_f32_16x16x32_bf16 v[84:87], v[154:157], v[204:207], v[84:87]
	s_waitcnt lgkmcnt(1)
	v_mfma_f32_16x16x32_bf16 v[76:79], v[138:141], v[212:215], v[76:79]
	v_mfma_f32_16x16x32_bf16 v[64:67], v[154:157], v[212:215], v[64:67]
	v_mfma_f32_16x16x32_bf16 v[124:127], v[142:145], v[184:187], v[124:127]
	v_mfma_f32_16x16x32_bf16 v[116:119], v[158:161], v[184:187], v[116:119]
	v_mfma_f32_16x16x32_bf16 v[108:111], v[142:145], v[200:203], v[108:111]
	v_mfma_f32_16x16x32_bf16 v[100:103], v[158:161], v[200:203], v[100:103]
	v_mfma_f32_16x16x32_bf16 v[92:95], v[142:145], v[208:211], v[92:95]
	v_mfma_f32_16x16x32_bf16 v[84:87], v[158:161], v[208:211], v[84:87]
	s_waitcnt lgkmcnt(0)
	v_mfma_f32_16x16x32_bf16 v[76:79], v[142:145], v[216:219], v[76:79]
	v_mfma_f32_16x16x32_bf16 v[64:67], v[158:161], v[216:219], v[64:67]
	s_setprio 0
	s_setprio 1
	v_mfma_f32_16x16x32_bf16 v[128:131], v[162:165], v[180:183], v[128:131]
	v_mfma_f32_16x16x32_bf16 v[120:123], v[172:175], v[180:183], v[120:123]
	v_mfma_f32_16x16x32_bf16 v[112:115], v[162:165], v[196:199], v[112:115]
	v_mfma_f32_16x16x32_bf16 v[104:107], v[172:175], v[196:199], v[104:107]
	v_mfma_f32_16x16x32_bf16 v[96:99], v[162:165], v[204:207], v[96:99]
	v_mfma_f32_16x16x32_bf16 v[88:91], v[172:175], v[204:207], v[88:91]
	v_mfma_f32_16x16x32_bf16 v[80:83], v[162:165], v[212:215], v[80:83]
	v_mfma_f32_16x16x32_bf16 v[72:75], v[172:175], v[212:215], v[72:75]
	v_mfma_f32_16x16x32_bf16 v[128:131], v[166:169], v[184:187], v[128:131]
	v_mfma_f32_16x16x32_bf16 v[120:123], v[176:179], v[184:187], v[120:123]
	v_mfma_f32_16x16x32_bf16 v[112:115], v[166:169], v[200:203], v[112:115]
	v_mfma_f32_16x16x32_bf16 v[104:107], v[176:179], v[200:203], v[104:107]
	v_mfma_f32_16x16x32_bf16 v[96:99], v[166:169], v[208:211], v[96:99]
	v_mfma_f32_16x16x32_bf16 v[88:91], v[176:179], v[208:211], v[88:91]
	v_mfma_f32_16x16x32_bf16 v[80:83], v[166:169], v[216:219], v[80:83]
	v_mfma_f32_16x16x32_bf16 v[72:75], v[176:179], v[216:219], v[72:75]
	s_barrier
	s_setprio 0
	ds_read_b128 v[180:183], v152 offset:49152
	ds_read_b128 v[184:187], v152 offset:50176
	ds_read_b128 v[196:199], v152 offset:51200
	ds_read_b128 v[200:203], v152 offset:52224
	ds_read_b128 v[204:207], v152 offset:53248
	ds_read_b128 v[208:211], v152 offset:54272
	ds_read_b128 v[212:215], v152 offset:55296
	ds_read_b128 v[216:219], v152 offset:56320
	s_add_i32 m0, s69, 0x18000
	s_nop 0
	global_load_lds_dwordx4 v1, s[86:87]
	s_nop 0
	s_add_i32 m0, s69, 0x1a000
	s_nop 0
	global_load_lds_dwordx4 v146, s[86:87]
	s_add_u32 s2, s2, 0x40080
	s_addc_u32 s3, s3, 0
	s_add_i32 m0, s69, 0x1c000
	s_nop 0
	global_load_lds_dwordx4 v1, s[2:3]
	s_nop 0
	s_add_i32 m0, s69, 0x1e000
	s_nop 0
	global_load_lds_dwordx4 v146, s[2:3]
	s_nop 0
	s_add_i32 m0, s69, 0x8000
	s_nop 0
	global_load_lds_dwordx4 v147, s[12:13]
	s_nop 0
	s_add_i32 m0, s69, 0xa000
	s_nop 0
	global_load_lds_dwordx4 v148, s[12:13]
	s_waitcnt vmcnt(8)
	s_waitcnt lgkmcnt(0)
	s_setprio 1
	s_barrier
	v_mfma_f32_16x16x32_bf16 v[60:63], v[138:141], v[180:183], v[60:63]
	v_mfma_f32_16x16x32_bf16 v[52:55], v[154:157], v[180:183], v[52:55]
	s_waitcnt lgkmcnt(5)
	v_mfma_f32_16x16x32_bf16 v[44:47], v[138:141], v[196:199], v[44:47]
	v_mfma_f32_16x16x32_bf16 v[36:39], v[154:157], v[196:199], v[36:39]
	s_waitcnt lgkmcnt(3)
	v_mfma_f32_16x16x32_bf16 v[28:31], v[138:141], v[204:207], v[28:31]
	v_mfma_f32_16x16x32_bf16 v[20:23], v[154:157], v[204:207], v[20:23]
	s_waitcnt lgkmcnt(1)
	v_mfma_f32_16x16x32_bf16 v[12:15], v[138:141], v[212:215], v[12:15]
	v_mfma_f32_16x16x32_bf16 v[4:7], v[154:157], v[212:215], v[4:7]
	v_mfma_f32_16x16x32_bf16 v[60:63], v[142:145], v[184:187], v[60:63]
	v_mfma_f32_16x16x32_bf16 v[52:55], v[158:161], v[184:187], v[52:55]
	v_mfma_f32_16x16x32_bf16 v[44:47], v[142:145], v[200:203], v[44:47]
	v_mfma_f32_16x16x32_bf16 v[36:39], v[158:161], v[200:203], v[36:39]
	v_mfma_f32_16x16x32_bf16 v[28:31], v[142:145], v[208:211], v[28:31]
	v_mfma_f32_16x16x32_bf16 v[20:23], v[158:161], v[208:211], v[20:23]
	s_waitcnt lgkmcnt(0)
	v_mfma_f32_16x16x32_bf16 v[12:15], v[142:145], v[216:219], v[12:15]
	v_mfma_f32_16x16x32_bf16 v[4:7], v[158:161], v[216:219], v[4:7]
	s_setprio 0
	s_setprio 1
	v_mfma_f32_16x16x32_bf16 v[68:71], v[162:165], v[180:183], v[68:71]
	v_mfma_f32_16x16x32_bf16 v[56:59], v[172:175], v[180:183], v[56:59]
	v_mfma_f32_16x16x32_bf16 v[48:51], v[162:165], v[196:199], v[48:51]
	v_mfma_f32_16x16x32_bf16 v[40:43], v[172:175], v[196:199], v[40:43]
	v_mfma_f32_16x16x32_bf16 v[32:35], v[162:165], v[204:207], v[32:35]
	v_mfma_f32_16x16x32_bf16 v[24:27], v[172:175], v[204:207], v[24:27]
	v_mfma_f32_16x16x32_bf16 v[16:19], v[162:165], v[212:215], v[16:19]
	v_mfma_f32_16x16x32_bf16 v[8:11], v[172:175], v[212:215], v[8:11]
	v_mfma_f32_16x16x32_bf16 v[68:71], v[166:169], v[184:187], v[68:71]
	v_mfma_f32_16x16x32_bf16 v[56:59], v[176:179], v[184:187], v[56:59]
	v_mfma_f32_16x16x32_bf16 v[48:51], v[166:169], v[200:203], v[48:51]
	v_mfma_f32_16x16x32_bf16 v[40:43], v[176:179], v[200:203], v[40:43]
	v_mfma_f32_16x16x32_bf16 v[32:35], v[166:169], v[208:211], v[32:35]
	v_mfma_f32_16x16x32_bf16 v[24:27], v[176:179], v[208:211], v[24:27]
	v_mfma_f32_16x16x32_bf16 v[16:19], v[166:169], v[216:219], v[16:19]
	v_mfma_f32_16x16x32_bf16 v[8:11], v[176:179], v[216:219], v[8:11]
	s_barrier
	s_setprio 0
	s_add_i32 s2, s29, 2
	s_cmp_gt_u32 s29, 13
	s_cbranch_scc1 .LBB0_1196
	s_mov_b32 s29, s2
	s_branch .LBB0_1072
